# EpiResid epilogues: lane^32 half of the row sum-of-squares via copy + v_permlane32_swap instead of ds_bpermute with rebuilt address
# baseline (speedup 1.0000x reference)
.LBB0_801:
	s_mov_b32 s15, s93
	s_mov_b32 s18, s33
	v_mov_b32_e32 v138, s15
	ds_read2_b32 v[138:139], v138 offset1:1
	s_mov_b32 s15, s92
	s_ashr_i32 s15, s14, 31
	s_lshl_b64 s[14:15], s[14:15], 8
	s_waitcnt lgkmcnt(0)
	v_readfirstlane_b32 s16, v138
	v_lshl_or_b32 v138, s43, 8, v155
	v_lshl_add_u64 v[140:141], s[14:15], 0, v[132:133]
	v_readfirstlane_b32 s17, v139
	v_ashrrev_i32_e32 v139, 31, v138
	v_lshlrev_b64 v[144:145], 11, v[140:141]
	v_lshl_add_u64 v[142:143], s[16:17], 0, v[144:145]
	v_lshlrev_b64 v[146:147], 1, v[138:139]
	s_mov_b32 s18, s33
	v_lshl_add_u64 v[158:159], v[142:143], 0, v[146:147]
	global_load_dwordx2 v[160:161], v[158:159], off
	global_load_dwordx2 v[162:163], v[158:159], off offset:32
	global_load_dwordx2 v[164:165], v[158:159], off offset:256
	global_load_dwordx2 v[166:167], v[158:159], off offset:288
	v_mov_b32_e32 v142, s18
	ds_read2_b32 v[148:149], v142 offset1:1
	v_lshl_add_u64 v[142:143], s[16:17], 0, v[146:147]
	v_lshl_add_u64 v[144:145], v[142:143], 0, v[144:145]
	v_add_co_u32_e32 v146, vcc, s50, v144
	s_waitcnt lgkmcnt(0)
	v_readfirstlane_b32 s18, v148
	v_addc_co_u32_e32 v147, vcc, 0, v145, vcc
	v_readfirstlane_b32 s19, v149
	global_load_dwordx2 v[152:153], v[146:147], off
	global_load_dwordx2 v[150:151], v[146:147], off offset:32
	global_load_dwordx2 v[148:149], v[146:147], off offset:256
	s_nop 0
	global_load_dwordx2 v[146:147], v[146:147], off offset:288
	s_lshl_b32 s14, s43, 2
	s_ashr_i32 s15, s14, 31
	s_lshl_b64 s[14:15], s[14:15], 2
	s_add_u32 s14, s18, s14
	s_addc_u32 s15, s19, s15
	s_add_u32 s14, s14, s40
	s_addc_u32 s15, s15, 0
	s_add_u32 s14, s14, 0x10380000
	s_addc_u32 s15, s15, 0
	s_waitcnt vmcnt(0)
	v_cvt_f32_f16_e32 v168, v160
	v_cvt_f32_f16_sdwa v169, v160 dst_sel:DWORD dst_unused:UNUSED_PAD src0_sel:WORD_1
	v_cvt_f32_f16_e32 v160, v161
	v_cvt_f32_f16_sdwa v161, v161 dst_sel:DWORD dst_unused:UNUSED_PAD src0_sel:WORD_1
	v_cvt_f32_f16_e32 v170, v162
	v_cvt_f32_f16_sdwa v171, v162 dst_sel:DWORD dst_unused:UNUSED_PAD src0_sel:WORD_1
	v_cvt_f32_f16_e32 v162, v163
	v_cvt_f32_f16_sdwa v163, v163 dst_sel:DWORD dst_unused:UNUSED_PAD src0_sel:WORD_1
	v_cvt_f32_f16_e32 v172, v164
	v_cvt_f32_f16_sdwa v173, v164 dst_sel:DWORD dst_unused:UNUSED_PAD src0_sel:WORD_1
	v_cvt_f32_f16_e32 v164, v165
	v_cvt_f32_f16_sdwa v165, v165 dst_sel:DWORD dst_unused:UNUSED_PAD src0_sel:WORD_1
	v_cvt_f32_f16_e32 v174, v166
	v_cvt_f32_f16_sdwa v175, v166 dst_sel:DWORD dst_unused:UNUSED_PAD src0_sel:WORD_1
	v_cvt_f32_f16_e32 v166, v167
	v_cvt_f32_f16_sdwa v167, v167 dst_sel:DWORD dst_unused:UNUSED_PAD src0_sel:WORD_1
	v_pk_fma_f32 v[128:129], v[128:129], 0.5, v[160:161] op_sel_hi:[1,0,1]
	v_pk_fma_f32 v[126:127], v[126:127], 0.5, v[168:169] op_sel_hi:[1,0,1]
	v_pk_fma_f32 v[122:123], v[122:123], 0.5, v[170:171] op_sel_hi:[1,0,1]
	v_pk_fma_f32 v[124:125], v[124:125], 0.5, v[162:163] op_sel_hi:[1,0,1]
	v_pk_fma_f32 v[120:121], v[120:121], 0.5, v[164:165] op_sel_hi:[1,0,1]
	v_pk_fma_f32 v[118:119], v[118:119], 0.5, v[172:173] op_sel_hi:[1,0,1]
	v_cvt_f16_f32_e32 v157, v126
	v_cvt_f16_f32_sdwa v160, v127 dst_sel:WORD_1 dst_unused:UNUSED_PAD src0_sel:DWORD
	v_cvt_f16_f32_e32 v161, v128
	v_cvt_f16_f32_sdwa v162, v129 dst_sel:WORD_1 dst_unused:UNUSED_PAD src0_sel:DWORD
	v_cvt_f16_f32_e32 v163, v122
	v_cvt_f16_f32_sdwa v164, v123 dst_sel:WORD_1 dst_unused:UNUSED_PAD src0_sel:DWORD
	v_pk_fma_f32 v[116:117], v[116:117], 0.5, v[166:167] op_sel_hi:[1,0,1]
	v_mul_f32_e32 v127, v127, v127
	v_mul_f32_e32 v129, v129, v129
	v_cvt_f16_f32_e32 v165, v124
	v_cvt_f16_f32_sdwa v166, v125 dst_sel:WORD_1 dst_unused:UNUSED_PAD src0_sel:DWORD
	v_mul_f32_e32 v123, v123, v123
	v_mul_f32_e32 v125, v125, v125
	v_cvt_f16_f32_e32 v167, v118
	v_cvt_f16_f32_sdwa v168, v119 dst_sel:WORD_1 dst_unused:UNUSED_PAD src0_sel:DWORD
	v_cvt_f16_f32_e32 v169, v120
	v_cvt_f16_f32_sdwa v170, v121 dst_sel:WORD_1 dst_unused:UNUSED_PAD src0_sel:DWORD
	v_mul_f32_e32 v171, v119, v119
	v_fmac_f32_e32 v127, v126, v126
	v_fmac_f32_e32 v129, v128, v128
	v_fmac_f32_e32 v123, v122, v122
	v_fmac_f32_e32 v125, v124, v124
	v_mul_f32_e32 v172, v121, v121
	v_fmac_f32_e32 v171, v118, v118
	v_add_f32_e32 v118, v127, v129
	v_add_f32_e32 v119, v123, v125
	v_pk_fma_f32 v[114:115], v[114:115], 0.5, v[174:175] op_sel_hi:[1,0,1]
	v_fmac_f32_e32 v172, v120, v120
	v_add_f32_e32 v124, v118, v119
	v_or_b32_e32 v118, v160, v157
	v_or_b32_e32 v119, v162, v161
	v_or_b32_e32 v120, v164, v163
	v_cvt_f16_f32_e32 v173, v114
	v_cvt_f16_f32_sdwa v174, v115 dst_sel:WORD_1 dst_unused:UNUSED_PAD src0_sel:DWORD
	v_or_b32_e32 v121, v166, v165
	v_or_b32_e32 v122, v168, v167
	v_or_b32_e32 v123, v170, v169
	v_mov_b32_e32 v240, v118
	v_mov_b32_e32 v241, v119
	v_mov_b32_e32 v242, v120
	v_mov_b32_e32 v243, v121
	v_mbcnt_lo_u32_b32 v222, -1, 0
	v_mbcnt_hi_u32_b32 v222, -1, v222
	v_bfe_u32 v222, v222, 4, 1
	v_mul_u32_u24_e32 v222, 24, v222
	v_mov_b32_e32 v223, 0
	v_permlane16_swap_b32_e32 v240, v242
	v_permlane16_swap_b32_e32 v241, v243
	v_lshl_add_u64 v[222:223], v[158:159], 0, v[222:223]
	global_store_dwordx4 v[222:223], v[240:243], off sc1
	v_mov_b32_e32 v244, v122
	v_mov_b32_e32 v245, v123
	v_cvt_f16_f32_e32 v119, v116
	v_cvt_f16_f32_sdwa v120, v117 dst_sel:WORD_1 dst_unused:UNUSED_PAD src0_sel:DWORD
	v_mul_f32_e32 v115, v115, v115
	v_fmac_f32_e32 v115, v114, v114
	v_mul_f32_e32 v114, v117, v117
	v_add_f32_e32 v118, v171, v172
	v_fmac_f32_e32 v114, v116, v116
	v_add_f32_e32 v121, v124, v118
	v_or_b32_e32 v118, v174, v173
	v_or_b32_e32 v119, v120, v119
	v_add_f32_e32 v114, v115, v114
	v_mov_b32_e32 v246, v118
	v_mov_b32_e32 v247, v119
	v_mbcnt_lo_u32_b32 v222, -1, 0
	v_mbcnt_hi_u32_b32 v222, -1, v222
	v_bfe_u32 v222, v222, 4, 1
	v_mul_u32_u24_e32 v222, 24, v222
	v_mov_b32_e32 v223, 0
	v_permlane16_swap_b32_e32 v244, v246
	v_permlane16_swap_b32_e32 v245, v247
	v_lshl_add_u64 v[222:223], v[158:159], 0, v[222:223]
	global_store_dwordx4 v[222:223], v[244:247], off offset:256 sc1
	v_add_f32_e32 v114, v121, v114
	v_mov_b32_e32 v115, v114
	s_nop 1
	v_permlane16_swap_b32_e32 v115, v114
	s_waitcnt lgkmcnt(0)
	v_add_f32_e32 v114, v114, v115
	s_nop 0
	v_mov_b32_e32 v115, v114
	s_nop 1
	v_permlane32_swap_b32_e32 v115, v114
	s_and_saveexec_b64 s[18:19], s[0:1]
	s_cbranch_execz .LBB0_803
	v_lshlrev_b64 v[116:117], 6, v[140:141]
	v_lshl_add_u64 v[116:117], s[14:15], 0, v[116:117]
	s_waitcnt lgkmcnt(0)
	v_add_f32_e32 v114, v114, v115
	global_store_dword v[116:117], v114, off
.LBB0_803:
	s_or_b64 exec, exec, s[18:19]
	v_cvt_f32_f16_sdwa v117, v152 dst_sel:DWORD dst_unused:UNUSED_PAD src0_sel:WORD_1
	v_cvt_f32_f16_e32 v116, v152
	v_cvt_f32_f16_sdwa v119, v153 dst_sel:DWORD dst_unused:UNUSED_PAD src0_sel:WORD_1
	v_cvt_f32_f16_e32 v118, v153
	s_mov_b32 s18, 0x10000
	v_cvt_f32_f16_sdwa v129, v146 dst_sel:DWORD dst_unused:UNUSED_PAD src0_sel:WORD_1
	v_cvt_f32_f16_e32 v128, v146
	v_add_co_u32_e32 v146, vcc, s18, v144
	v_cvt_f32_f16_sdwa v125, v148 dst_sel:DWORD dst_unused:UNUSED_PAD src0_sel:WORD_1
	v_cvt_f32_f16_e32 v124, v148
	v_cvt_f32_f16_sdwa v127, v149 dst_sel:DWORD dst_unused:UNUSED_PAD src0_sel:WORD_1
	v_cvt_f32_f16_e32 v126, v149
	v_cvt_f32_f16_sdwa v149, v147 dst_sel:DWORD dst_unused:UNUSED_PAD src0_sel:WORD_1
	v_cvt_f32_f16_e32 v148, v147
	v_addc_co_u32_e32 v147, vcc, 0, v145, vcc
	v_cvt_f32_f16_sdwa v121, v150 dst_sel:DWORD dst_unused:UNUSED_PAD src0_sel:WORD_1
	v_cvt_f32_f16_e32 v120, v150
	v_cvt_f32_f16_sdwa v123, v151 dst_sel:DWORD dst_unused:UNUSED_PAD src0_sel:WORD_1
	v_cvt_f32_f16_e32 v122, v151
	v_pk_fma_f32 v[150:151], v[112:113], 0.5, v[118:119] op_sel_hi:[1,0,1]
	v_pk_fma_f32 v[152:153], v[110:111], 0.5, v[116:117] op_sel_hi:[1,0,1]
	global_load_dwordx2 v[118:119], v[146:147], off
	global_load_dwordx2 v[116:117], v[146:147], off offset:32
	global_load_dwordx2 v[112:113], v[146:147], off offset:256
	global_load_dwordx2 v[110:111], v[146:147], off offset:288
	v_cvt_f16_f32_e32 v157, v152
	v_cvt_f16_f32_sdwa v158, v153 dst_sel:WORD_1 dst_unused:UNUSED_PAD src0_sel:DWORD
	v_cvt_f16_f32_e32 v159, v150
	v_cvt_f16_f32_sdwa v160, v151 dst_sel:WORD_1 dst_unused:UNUSED_PAD src0_sel:DWORD
	v_pk_fma_f32 v[108:109], v[108:109], 0.5, v[122:123] op_sel_hi:[1,0,1]
	v_pk_fma_f32 v[106:107], v[106:107], 0.5, v[120:121] op_sel_hi:[1,0,1]
	v_cvt_f16_f32_e32 v122, v108
	v_cvt_f16_f32_e32 v120, v106
	v_cvt_f16_f32_sdwa v121, v107 dst_sel:WORD_1 dst_unused:UNUSED_PAD src0_sel:DWORD
	v_cvt_f16_f32_sdwa v123, v109 dst_sel:WORD_1 dst_unused:UNUSED_PAD src0_sel:DWORD
	v_or_b32_e32 v114, 16, v140
	s_waitcnt lgkmcnt(0)
	v_mov_b32_e32 v115, v141
	v_or_b32_e32 v146, v158, v157
	v_or_b32_e32 v147, v160, v159
	v_lshlrev_b64 v[158:159], 11, v[114:115]
	v_lshl_add_u64 v[158:159], s[16:17], 0, v[158:159]
	v_mul_f32_e32 v107, v107, v107
	v_lshl_add_u64 v[158:159], v[138:139], 1, v[158:159]
	v_or_b32_e32 v120, v121, v120
	v_or_b32_e32 v121, v123, v122
	v_fmac_f32_e32 v107, v106, v106
	v_mul_f32_e32 v106, v109, v109
	v_pk_fma_f32 v[104:105], v[104:105], 0.5, v[126:127] op_sel_hi:[1,0,1]
	v_pk_fma_f32 v[102:103], v[102:103], 0.5, v[124:125] op_sel_hi:[1,0,1]
	v_mov_b32_e32 v242, v120
	v_mov_b32_e32 v243, v121
	v_fmac_f32_e32 v106, v108, v108
	v_cvt_f16_f32_e32 v108, v102
	v_cvt_f16_f32_sdwa v109, v103 dst_sel:WORD_1 dst_unused:UNUSED_PAD src0_sel:DWORD
	v_cvt_f16_f32_e32 v120, v104
	v_cvt_f16_f32_sdwa v121, v105 dst_sel:WORD_1 dst_unused:UNUSED_PAD src0_sel:DWORD
	v_mov_b32_e32 v240, v146
	v_mov_b32_e32 v241, v147
	v_mbcnt_lo_u32_b32 v222, -1, 0
	v_mbcnt_hi_u32_b32 v222, -1, v222
	v_bfe_u32 v222, v222, 4, 1
	v_mul_u32_u24_e32 v222, 24, v222
	v_mov_b32_e32 v223, 0
	v_permlane16_swap_b32_e32 v240, v242
	v_permlane16_swap_b32_e32 v241, v243
	v_lshl_add_u64 v[222:223], v[158:159], 0, v[222:223]
	global_store_dwordx4 v[222:223], v[240:243], off sc1
	v_mul_f32_e32 v146, v153, v153
	v_mul_f32_e32 v147, v151, v151
	v_fmac_f32_e32 v146, v152, v152
	v_fmac_f32_e32 v147, v150, v150
	v_add_f32_e32 v146, v146, v147
	v_add_f32_e32 v106, v107, v106
	v_mul_f32_e32 v103, v103, v103
	v_add_f32_e32 v122, v146, v106
	v_or_b32_e32 v106, v109, v108
	v_or_b32_e32 v107, v121, v120
	v_fmac_f32_e32 v103, v102, v102
	v_mul_f32_e32 v102, v105, v105
	v_pk_fma_f32 v[100:101], v[100:101], 0.5, v[148:149] op_sel_hi:[1,0,1]
	v_pk_fma_f32 v[98:99], v[98:99], 0.5, v[128:129] op_sel_hi:[1,0,1]
	v_mov_b32_e32 v244, v106
	v_mov_b32_e32 v245, v107
	v_fmac_f32_e32 v102, v104, v104
	v_cvt_f16_f32_e32 v104, v98
	v_cvt_f16_f32_sdwa v105, v99 dst_sel:WORD_1 dst_unused:UNUSED_PAD src0_sel:DWORD
	v_cvt_f16_f32_e32 v106, v100
	v_cvt_f16_f32_sdwa v107, v101 dst_sel:WORD_1 dst_unused:UNUSED_PAD src0_sel:DWORD
	v_mul_f32_e32 v99, v99, v99
	v_fmac_f32_e32 v99, v98, v98
	v_mul_f32_e32 v98, v101, v101
	v_add_f32_e32 v102, v103, v102
	v_fmac_f32_e32 v98, v100, v100
	v_add_f32_e32 v108, v122, v102
	v_or_b32_e32 v102, v105, v104
	v_or_b32_e32 v103, v107, v106
	v_add_f32_e32 v98, v99, v98
	v_mov_b32_e32 v246, v102
	v_mov_b32_e32 v247, v103
	v_mbcnt_lo_u32_b32 v222, -1, 0
	v_mbcnt_hi_u32_b32 v222, -1, v222
	v_bfe_u32 v222, v222, 4, 1
	v_mul_u32_u24_e32 v222, 24, v222
	v_mov_b32_e32 v223, 0
	v_permlane16_swap_b32_e32 v244, v246
	v_permlane16_swap_b32_e32 v245, v247
	v_lshl_add_u64 v[222:223], v[158:159], 0, v[222:223]
	global_store_dwordx4 v[222:223], v[244:247], off offset:256 sc1
	v_add_f32_e32 v98, v108, v98
	v_mov_b32_e32 v99, v98
	s_nop 1
	v_permlane16_swap_b32_e32 v99, v98
	s_waitcnt lgkmcnt(0)
	v_add_f32_e32 v98, v98, v99
	s_nop 0
	v_mov_b32_e32 v99, v98
	s_nop 1
	v_permlane32_swap_b32_e32 v99, v98
	s_and_saveexec_b64 s[18:19], s[0:1]
	s_cbranch_execz .LBB0_805
	v_lshlrev_b64 v[100:101], 6, v[114:115]
	v_lshl_add_u64 v[100:101], s[14:15], 0, v[100:101]
	s_waitcnt lgkmcnt(0)
	v_add_f32_e32 v98, v98, v99
	global_store_dword v[100:101], v98, off
.LBB0_805:
	s_or_b64 exec, exec, s[18:19]
	s_waitcnt vmcnt(5)
	v_cvt_f32_f16_sdwa v101, v118 dst_sel:DWORD dst_unused:UNUSED_PAD src0_sel:WORD_1
	v_cvt_f32_f16_e32 v100, v118
	v_cvt_f32_f16_sdwa v103, v119 dst_sel:DWORD dst_unused:UNUSED_PAD src0_sel:WORD_1
	v_cvt_f32_f16_e32 v102, v119
	s_mov_b32 s18, 0x18000
	s_waitcnt vmcnt(3)
	v_cvt_f32_f16_sdwa v109, v112 dst_sel:DWORD dst_unused:UNUSED_PAD src0_sel:WORD_1
	v_cvt_f32_f16_e32 v108, v112
	v_cvt_f32_f16_sdwa v115, v113 dst_sel:DWORD dst_unused:UNUSED_PAD src0_sel:WORD_1
	v_cvt_f32_f16_e32 v114, v113
	s_waitcnt vmcnt(2)
	v_cvt_f32_f16_sdwa v113, v110 dst_sel:DWORD dst_unused:UNUSED_PAD src0_sel:WORD_1
	v_cvt_f32_f16_e32 v112, v110
	v_add_co_u32_e32 v110, vcc, s18, v144
	v_cvt_f32_f16_sdwa v105, v116 dst_sel:DWORD dst_unused:UNUSED_PAD src0_sel:WORD_1
	v_cvt_f32_f16_e32 v104, v116
	v_cvt_f32_f16_sdwa v107, v117 dst_sel:DWORD dst_unused:UNUSED_PAD src0_sel:WORD_1
	v_cvt_f32_f16_e32 v106, v117
	v_cvt_f32_f16_sdwa v117, v111 dst_sel:DWORD dst_unused:UNUSED_PAD src0_sel:WORD_1
	v_cvt_f32_f16_e32 v116, v111
	v_addc_co_u32_e32 v111, vcc, 0, v145, vcc
	v_pk_fma_f32 v[118:119], v[96:97], 0.5, v[102:103] op_sel_hi:[1,0,1]
	v_pk_fma_f32 v[120:121], v[94:95], 0.5, v[100:101] op_sel_hi:[1,0,1]
	global_load_dwordx2 v[102:103], v[110:111], off
	global_load_dwordx2 v[100:101], v[110:111], off offset:32
	global_load_dwordx2 v[96:97], v[110:111], off offset:256
	global_load_dwordx2 v[94:95], v[110:111], off offset:288
	v_cvt_f16_f32_e32 v122, v120
	v_cvt_f16_f32_sdwa v123, v121 dst_sel:WORD_1 dst_unused:UNUSED_PAD src0_sel:DWORD
	v_pk_fma_f32 v[92:93], v[92:93], 0.5, v[106:107] op_sel_hi:[1,0,1]
	v_pk_fma_f32 v[90:91], v[90:91], 0.5, v[104:105] op_sel_hi:[1,0,1]
	v_cvt_f16_f32_e32 v106, v92
	v_cvt_f16_f32_e32 v104, v90
	v_cvt_f16_f32_sdwa v105, v91 dst_sel:WORD_1 dst_unused:UNUSED_PAD src0_sel:DWORD
	v_cvt_f16_f32_sdwa v107, v93 dst_sel:WORD_1 dst_unused:UNUSED_PAD src0_sel:DWORD
	v_or_b32_e32 v98, 32, v140
	s_waitcnt lgkmcnt(0)
	v_mov_b32_e32 v99, v141
	v_cvt_f16_f32_e32 v124, v118
	v_cvt_f16_f32_sdwa v125, v119 dst_sel:WORD_1 dst_unused:UNUSED_PAD src0_sel:DWORD
	v_or_b32_e32 v110, v123, v122
	v_lshlrev_b64 v[122:123], 11, v[98:99]
	v_lshl_add_u64 v[122:123], s[16:17], 0, v[122:123]
	v_mul_f32_e32 v91, v91, v91
	v_lshl_add_u64 v[122:123], v[138:139], 1, v[122:123]
	v_or_b32_e32 v104, v105, v104
	v_or_b32_e32 v105, v107, v106
	v_fmac_f32_e32 v91, v90, v90
	v_mul_f32_e32 v90, v93, v93
	v_pk_fma_f32 v[88:89], v[88:89], 0.5, v[114:115] op_sel_hi:[1,0,1]
	v_pk_fma_f32 v[86:87], v[86:87], 0.5, v[108:109] op_sel_hi:[1,0,1]
	v_or_b32_e32 v111, v125, v124
	v_mov_b32_e32 v242, v104
	v_mov_b32_e32 v243, v105
	v_fmac_f32_e32 v90, v92, v92
	v_cvt_f16_f32_e32 v92, v86
	v_cvt_f16_f32_sdwa v93, v87 dst_sel:WORD_1 dst_unused:UNUSED_PAD src0_sel:DWORD
	v_cvt_f16_f32_e32 v104, v88
	v_cvt_f16_f32_sdwa v105, v89 dst_sel:WORD_1 dst_unused:UNUSED_PAD src0_sel:DWORD
	v_mov_b32_e32 v240, v110
	v_mov_b32_e32 v241, v111
	v_mbcnt_lo_u32_b32 v222, -1, 0
	v_mbcnt_hi_u32_b32 v222, -1, v222
	v_bfe_u32 v222, v222, 4, 1
	v_mul_u32_u24_e32 v222, 24, v222
	v_mov_b32_e32 v223, 0
	v_permlane16_swap_b32_e32 v240, v242
	v_permlane16_swap_b32_e32 v241, v243
	v_lshl_add_u64 v[222:223], v[122:123], 0, v[222:223]
	global_store_dwordx4 v[222:223], v[240:243], off sc1
	v_mul_f32_e32 v110, v121, v121
	v_mul_f32_e32 v111, v119, v119
	v_fmac_f32_e32 v110, v120, v120
	v_fmac_f32_e32 v111, v118, v118
	v_add_f32_e32 v110, v110, v111
	v_add_f32_e32 v90, v91, v90
	v_mul_f32_e32 v87, v87, v87
	v_add_f32_e32 v106, v110, v90
	v_or_b32_e32 v90, v93, v92
	v_or_b32_e32 v91, v105, v104
	v_fmac_f32_e32 v87, v86, v86
	v_mul_f32_e32 v86, v89, v89
	v_pk_fma_f32 v[84:85], v[84:85], 0.5, v[116:117] op_sel_hi:[1,0,1]
	v_pk_fma_f32 v[82:83], v[82:83], 0.5, v[112:113] op_sel_hi:[1,0,1]
	v_mov_b32_e32 v244, v90
	v_mov_b32_e32 v245, v91
	v_fmac_f32_e32 v86, v88, v88
	v_cvt_f16_f32_e32 v88, v82
	v_cvt_f16_f32_sdwa v89, v83 dst_sel:WORD_1 dst_unused:UNUSED_PAD src0_sel:DWORD
	v_cvt_f16_f32_e32 v90, v84
	v_cvt_f16_f32_sdwa v91, v85 dst_sel:WORD_1 dst_unused:UNUSED_PAD src0_sel:DWORD
	v_mul_f32_e32 v83, v83, v83
	v_fmac_f32_e32 v83, v82, v82
	v_mul_f32_e32 v82, v85, v85
	v_add_f32_e32 v86, v87, v86
	v_fmac_f32_e32 v82, v84, v84
	v_add_f32_e32 v92, v106, v86
	v_or_b32_e32 v86, v89, v88
	v_or_b32_e32 v87, v91, v90
	v_add_f32_e32 v82, v83, v82
	v_mov_b32_e32 v246, v86
	v_mov_b32_e32 v247, v87
	v_mbcnt_lo_u32_b32 v222, -1, 0
	v_mbcnt_hi_u32_b32 v222, -1, v222
	v_bfe_u32 v222, v222, 4, 1
	v_mul_u32_u24_e32 v222, 24, v222
	v_mov_b32_e32 v223, 0
	v_permlane16_swap_b32_e32 v244, v246
	v_permlane16_swap_b32_e32 v245, v247
	v_lshl_add_u64 v[222:223], v[122:123], 0, v[222:223]
	global_store_dwordx4 v[222:223], v[244:247], off offset:256 sc1
	v_add_f32_e32 v82, v92, v82
	v_mov_b32_e32 v83, v82
	s_nop 1
	v_permlane16_swap_b32_e32 v83, v82
	s_waitcnt lgkmcnt(0)
	v_add_f32_e32 v82, v82, v83
	s_nop 0
	v_mov_b32_e32 v83, v82
	s_nop 1
	v_permlane32_swap_b32_e32 v83, v82
	s_and_saveexec_b64 s[18:19], s[0:1]
	s_cbranch_execz .LBB0_807
	v_lshlrev_b64 v[84:85], 6, v[98:99]
	v_lshl_add_u64 v[84:85], s[14:15], 0, v[84:85]
	s_waitcnt lgkmcnt(0)
	v_add_f32_e32 v82, v82, v83
	global_store_dword v[84:85], v82, off
.LBB0_807:
	s_or_b64 exec, exec, s[18:19]
	s_waitcnt vmcnt(5)
	v_cvt_f32_f16_sdwa v85, v102 dst_sel:DWORD dst_unused:UNUSED_PAD src0_sel:WORD_1
	v_cvt_f32_f16_e32 v84, v102
	v_cvt_f32_f16_sdwa v87, v103 dst_sel:DWORD dst_unused:UNUSED_PAD src0_sel:WORD_1
	v_cvt_f32_f16_e32 v86, v103
	s_mov_b32 s18, 0x40000
	s_waitcnt vmcnt(3)
	v_cvt_f32_f16_sdwa v93, v96 dst_sel:DWORD dst_unused:UNUSED_PAD src0_sel:WORD_1
	v_cvt_f32_f16_e32 v92, v96
	v_cvt_f32_f16_sdwa v99, v97 dst_sel:DWORD dst_unused:UNUSED_PAD src0_sel:WORD_1
	v_cvt_f32_f16_e32 v98, v97
	s_waitcnt vmcnt(2)
	v_cvt_f32_f16_sdwa v97, v94 dst_sel:DWORD dst_unused:UNUSED_PAD src0_sel:WORD_1
	v_cvt_f32_f16_e32 v96, v94
	v_add_co_u32_e32 v94, vcc, s18, v144
	v_cvt_f32_f16_sdwa v89, v100 dst_sel:DWORD dst_unused:UNUSED_PAD src0_sel:WORD_1
	v_cvt_f32_f16_e32 v88, v100
	v_cvt_f32_f16_sdwa v91, v101 dst_sel:DWORD dst_unused:UNUSED_PAD src0_sel:WORD_1
	v_cvt_f32_f16_e32 v90, v101
	v_cvt_f32_f16_sdwa v101, v95 dst_sel:DWORD dst_unused:UNUSED_PAD src0_sel:WORD_1
	v_cvt_f32_f16_e32 v100, v95
	v_addc_co_u32_e32 v95, vcc, 0, v145, vcc
	v_pk_fma_f32 v[102:103], v[80:81], 0.5, v[86:87] op_sel_hi:[1,0,1]
	v_pk_fma_f32 v[104:105], v[78:79], 0.5, v[84:85] op_sel_hi:[1,0,1]
	global_load_dwordx2 v[86:87], v[94:95], off
	global_load_dwordx2 v[84:85], v[94:95], off offset:32
	global_load_dwordx2 v[80:81], v[94:95], off offset:256
	global_load_dwordx2 v[78:79], v[94:95], off offset:288
	v_cvt_f16_f32_e32 v106, v104
	v_cvt_f16_f32_sdwa v107, v105 dst_sel:WORD_1 dst_unused:UNUSED_PAD src0_sel:DWORD
	v_pk_fma_f32 v[76:77], v[76:77], 0.5, v[90:91] op_sel_hi:[1,0,1]
	v_pk_fma_f32 v[74:75], v[74:75], 0.5, v[88:89] op_sel_hi:[1,0,1]
	v_cvt_f16_f32_e32 v90, v76
	v_cvt_f16_f32_e32 v88, v74
	v_cvt_f16_f32_sdwa v89, v75 dst_sel:WORD_1 dst_unused:UNUSED_PAD src0_sel:DWORD
	v_cvt_f16_f32_sdwa v91, v77 dst_sel:WORD_1 dst_unused:UNUSED_PAD src0_sel:DWORD
	v_or_b32_e32 v82, 48, v140
	s_waitcnt lgkmcnt(0)
	v_mov_b32_e32 v83, v141
	v_cvt_f16_f32_e32 v108, v102
	v_cvt_f16_f32_sdwa v109, v103 dst_sel:WORD_1 dst_unused:UNUSED_PAD src0_sel:DWORD
	v_or_b32_e32 v94, v107, v106
	v_lshlrev_b64 v[106:107], 11, v[82:83]
	v_lshl_add_u64 v[106:107], s[16:17], 0, v[106:107]
	v_mul_f32_e32 v75, v75, v75
	v_lshl_add_u64 v[106:107], v[138:139], 1, v[106:107]
	v_or_b32_e32 v88, v89, v88
	v_or_b32_e32 v89, v91, v90
	v_fmac_f32_e32 v75, v74, v74
	v_mul_f32_e32 v74, v77, v77
	v_pk_fma_f32 v[72:73], v[72:73], 0.5, v[98:99] op_sel_hi:[1,0,1]
	v_pk_fma_f32 v[70:71], v[70:71], 0.5, v[92:93] op_sel_hi:[1,0,1]
	v_or_b32_e32 v95, v109, v108
	v_mov_b32_e32 v242, v88
	v_mov_b32_e32 v243, v89
	v_fmac_f32_e32 v74, v76, v76
	v_cvt_f16_f32_e32 v76, v70
	v_cvt_f16_f32_sdwa v77, v71 dst_sel:WORD_1 dst_unused:UNUSED_PAD src0_sel:DWORD
	v_cvt_f16_f32_e32 v88, v72
	v_cvt_f16_f32_sdwa v89, v73 dst_sel:WORD_1 dst_unused:UNUSED_PAD src0_sel:DWORD
	v_mov_b32_e32 v240, v94
	v_mov_b32_e32 v241, v95
	v_mbcnt_lo_u32_b32 v222, -1, 0
	v_mbcnt_hi_u32_b32 v222, -1, v222
	v_bfe_u32 v222, v222, 4, 1
	v_mul_u32_u24_e32 v222, 24, v222
	v_mov_b32_e32 v223, 0
	v_permlane16_swap_b32_e32 v240, v242
	v_permlane16_swap_b32_e32 v241, v243
	v_lshl_add_u64 v[222:223], v[106:107], 0, v[222:223]
	global_store_dwordx4 v[222:223], v[240:243], off sc1
	v_mul_f32_e32 v94, v105, v105
	v_mul_f32_e32 v95, v103, v103
	v_fmac_f32_e32 v94, v104, v104
	v_fmac_f32_e32 v95, v102, v102
	v_add_f32_e32 v94, v94, v95
	v_add_f32_e32 v74, v75, v74
	v_mul_f32_e32 v71, v71, v71
	v_add_f32_e32 v90, v94, v74
	v_or_b32_e32 v74, v77, v76
	v_or_b32_e32 v75, v89, v88
	v_fmac_f32_e32 v71, v70, v70
	v_mul_f32_e32 v70, v73, v73
	v_pk_fma_f32 v[68:69], v[68:69], 0.5, v[100:101] op_sel_hi:[1,0,1]
	v_pk_fma_f32 v[66:67], v[66:67], 0.5, v[96:97] op_sel_hi:[1,0,1]
	v_mov_b32_e32 v244, v74
	v_mov_b32_e32 v245, v75
	v_fmac_f32_e32 v70, v72, v72
	v_cvt_f16_f32_e32 v72, v66
	v_cvt_f16_f32_sdwa v73, v67 dst_sel:WORD_1 dst_unused:UNUSED_PAD src0_sel:DWORD
	v_cvt_f16_f32_e32 v74, v68
	v_cvt_f16_f32_sdwa v75, v69 dst_sel:WORD_1 dst_unused:UNUSED_PAD src0_sel:DWORD
	v_mul_f32_e32 v67, v67, v67
	v_fmac_f32_e32 v67, v66, v66
	v_mul_f32_e32 v66, v69, v69
	v_add_f32_e32 v70, v71, v70
	v_fmac_f32_e32 v66, v68, v68
	v_add_f32_e32 v76, v90, v70
	v_or_b32_e32 v70, v73, v72
	v_or_b32_e32 v71, v75, v74
	v_add_f32_e32 v66, v67, v66
	v_mov_b32_e32 v246, v70
	v_mov_b32_e32 v247, v71
	v_mbcnt_lo_u32_b32 v222, -1, 0
	v_mbcnt_hi_u32_b32 v222, -1, v222
	v_bfe_u32 v222, v222, 4, 1
	v_mul_u32_u24_e32 v222, 24, v222
	v_mov_b32_e32 v223, 0
	v_permlane16_swap_b32_e32 v244, v246
	v_permlane16_swap_b32_e32 v245, v247
	v_lshl_add_u64 v[222:223], v[106:107], 0, v[222:223]
	global_store_dwordx4 v[222:223], v[244:247], off offset:256 sc1
	v_add_f32_e32 v66, v76, v66
	v_mov_b32_e32 v67, v66
	s_nop 1
	v_permlane16_swap_b32_e32 v67, v66
	s_waitcnt lgkmcnt(0)
	v_add_f32_e32 v66, v66, v67
	s_nop 0
	v_mov_b32_e32 v67, v66
	s_nop 1
	v_permlane32_swap_b32_e32 v67, v66
	s_and_saveexec_b64 s[18:19], s[0:1]
	s_cbranch_execz .LBB0_809
	v_lshlrev_b64 v[68:69], 6, v[82:83]
	v_lshl_add_u64 v[68:69], s[14:15], 0, v[68:69]
	s_waitcnt lgkmcnt(0)
	v_add_f32_e32 v66, v66, v67
	global_store_dword v[68:69], v66, off
.LBB0_809:
	s_or_b64 exec, exec, s[18:19]
	s_waitcnt vmcnt(5)
	v_cvt_f32_f16_sdwa v71, v86 dst_sel:DWORD dst_unused:UNUSED_PAD src0_sel:WORD_1
	v_cvt_f32_f16_e32 v70, v86
	v_cvt_f32_f16_sdwa v73, v87 dst_sel:DWORD dst_unused:UNUSED_PAD src0_sel:WORD_1
	v_cvt_f32_f16_e32 v72, v87
	v_lshl_add_u64 v[68:69], v[140:141], 0, s[96:97]
	s_waitcnt lgkmcnt(0)
	v_lshlrev_b64 v[66:67], 11, v[68:69]
	v_or_b32_e32 v88, 0x8000, v66
	v_mov_b32_e32 v89, v67
	v_lshl_add_u64 v[88:89], v[142:143], 0, v[88:89]
	v_pk_fma_f32 v[90:91], v[64:65], 0.5, v[72:73] op_sel_hi:[1,0,1]
	v_pk_fma_f32 v[92:93], v[62:63], 0.5, v[70:71] op_sel_hi:[1,0,1]
	global_load_dwordx2 v[72:73], v[88:89], off
	global_load_dwordx2 v[70:71], v[88:89], off offset:32
	global_load_dwordx2 v[64:65], v[88:89], off offset:256
	global_load_dwordx2 v[62:63], v[88:89], off offset:288
	s_waitcnt vmcnt(8)
	v_cvt_f32_f16_sdwa v75, v84 dst_sel:DWORD dst_unused:UNUSED_PAD src0_sel:WORD_1
	v_cvt_f32_f16_e32 v74, v84
	v_cvt_f32_f16_sdwa v77, v85 dst_sel:DWORD dst_unused:UNUSED_PAD src0_sel:WORD_1
	v_cvt_f32_f16_e32 v76, v85
	s_waitcnt vmcnt(7)
	v_cvt_f32_f16_sdwa v83, v80 dst_sel:DWORD dst_unused:UNUSED_PAD src0_sel:WORD_1
	v_pk_fma_f32 v[58:59], v[58:59], 0.5, v[74:75] op_sel_hi:[1,0,1]
	v_cvt_f32_f16_e32 v82, v80
	v_pk_fma_f32 v[60:61], v[60:61], 0.5, v[76:77] op_sel_hi:[1,0,1]
	v_cvt_f32_f16_sdwa v85, v81 dst_sel:DWORD dst_unused:UNUSED_PAD src0_sel:WORD_1
	v_cvt_f32_f16_e32 v84, v81
	v_cvt_f16_f32_e32 v74, v58
	v_cvt_f16_f32_sdwa v75, v59 dst_sel:WORD_1 dst_unused:UNUSED_PAD src0_sel:DWORD
	v_cvt_f16_f32_e32 v76, v60
	v_cvt_f16_f32_sdwa v77, v61 dst_sel:WORD_1 dst_unused:UNUSED_PAD src0_sel:DWORD
	s_waitcnt vmcnt(6)
	v_cvt_f32_f16_sdwa v81, v78 dst_sel:DWORD dst_unused:UNUSED_PAD src0_sel:WORD_1
	v_cvt_f32_f16_e32 v80, v78
	v_cvt_f16_f32_e32 v78, v92
	v_cvt_f16_f32_sdwa v94, v93 dst_sel:WORD_1 dst_unused:UNUSED_PAD src0_sel:DWORD
	v_cvt_f16_f32_e32 v95, v90
	v_cvt_f16_f32_sdwa v96, v91 dst_sel:WORD_1 dst_unused:UNUSED_PAD src0_sel:DWORD
	v_lshl_add_u64 v[88:89], s[16:17], 0, v[66:67]
	v_mul_f32_e32 v59, v59, v59
	v_lshl_add_u64 v[88:89], v[138:139], 1, v[88:89]
	v_or_b32_e32 v74, v75, v74
	v_or_b32_e32 v75, v77, v76
	v_fmac_f32_e32 v59, v58, v58
	v_mul_f32_e32 v58, v61, v61
	v_pk_fma_f32 v[56:57], v[56:57], 0.5, v[84:85] op_sel_hi:[1,0,1]
	v_pk_fma_f32 v[54:55], v[54:55], 0.5, v[82:83] op_sel_hi:[1,0,1]
	v_cvt_f32_f16_sdwa v87, v79 dst_sel:DWORD dst_unused:UNUSED_PAD src0_sel:WORD_1
	v_cvt_f32_f16_e32 v86, v79
	v_or_b32_e32 v78, v94, v78
	v_or_b32_e32 v79, v96, v95
	v_mov_b32_e32 v242, v74
	v_mov_b32_e32 v243, v75
	v_fmac_f32_e32 v58, v60, v60
	v_cvt_f16_f32_e32 v60, v54
	v_cvt_f16_f32_sdwa v61, v55 dst_sel:WORD_1 dst_unused:UNUSED_PAD src0_sel:DWORD
	v_cvt_f16_f32_e32 v74, v56
	v_cvt_f16_f32_sdwa v75, v57 dst_sel:WORD_1 dst_unused:UNUSED_PAD src0_sel:DWORD
	v_mov_b32_e32 v240, v78
	v_mov_b32_e32 v241, v79
	v_mbcnt_lo_u32_b32 v222, -1, 0
	v_mbcnt_hi_u32_b32 v222, -1, v222
	v_bfe_u32 v222, v222, 4, 1
	v_mul_u32_u24_e32 v222, 24, v222
	v_mov_b32_e32 v223, 0
	v_permlane16_swap_b32_e32 v240, v242
	v_permlane16_swap_b32_e32 v241, v243
	v_lshl_add_u64 v[222:223], v[88:89], 0, v[222:223]
	global_store_dwordx4 v[222:223], v[240:243], off sc1
	v_mul_f32_e32 v78, v93, v93
	v_mul_f32_e32 v79, v91, v91
	v_fmac_f32_e32 v78, v92, v92
	v_fmac_f32_e32 v79, v90, v90
	v_add_f32_e32 v78, v78, v79
	v_add_f32_e32 v58, v59, v58
	v_mul_f32_e32 v55, v55, v55
	v_add_f32_e32 v76, v78, v58
	v_or_b32_e32 v58, v61, v60
	v_or_b32_e32 v59, v75, v74
	v_fmac_f32_e32 v55, v54, v54
	v_mul_f32_e32 v54, v57, v57
	v_pk_fma_f32 v[52:53], v[52:53], 0.5, v[86:87] op_sel_hi:[1,0,1]
	v_pk_fma_f32 v[50:51], v[50:51], 0.5, v[80:81] op_sel_hi:[1,0,1]
	v_mov_b32_e32 v244, v58
	v_mov_b32_e32 v245, v59
	v_fmac_f32_e32 v54, v56, v56
	v_cvt_f16_f32_e32 v56, v50
	v_cvt_f16_f32_sdwa v57, v51 dst_sel:WORD_1 dst_unused:UNUSED_PAD src0_sel:DWORD
	v_cvt_f16_f32_e32 v58, v52
	v_cvt_f16_f32_sdwa v59, v53 dst_sel:WORD_1 dst_unused:UNUSED_PAD src0_sel:DWORD
	v_mul_f32_e32 v51, v51, v51
	v_fmac_f32_e32 v51, v50, v50
	v_mul_f32_e32 v50, v53, v53
	v_add_f32_e32 v54, v55, v54
	v_fmac_f32_e32 v50, v52, v52
	v_add_f32_e32 v60, v76, v54
	v_or_b32_e32 v54, v57, v56
	v_or_b32_e32 v55, v59, v58
	v_add_f32_e32 v50, v51, v50
	v_mov_b32_e32 v246, v54
	v_mov_b32_e32 v247, v55
	v_mbcnt_lo_u32_b32 v222, -1, 0
	v_mbcnt_hi_u32_b32 v222, -1, v222
	v_bfe_u32 v222, v222, 4, 1
	v_mul_u32_u24_e32 v222, 24, v222
	v_mov_b32_e32 v223, 0
	v_permlane16_swap_b32_e32 v244, v246
	v_permlane16_swap_b32_e32 v245, v247
	v_lshl_add_u64 v[222:223], v[88:89], 0, v[222:223]
	global_store_dwordx4 v[222:223], v[244:247], off offset:256 sc1
	v_add_f32_e32 v50, v60, v50
	v_mov_b32_e32 v51, v50
	s_nop 1
	v_permlane16_swap_b32_e32 v51, v50
	s_waitcnt lgkmcnt(0)
	v_add_f32_e32 v50, v50, v51
	s_nop 0
	v_mov_b32_e32 v51, v50
	s_nop 1
	v_permlane32_swap_b32_e32 v51, v50
	s_and_saveexec_b64 s[18:19], s[0:1]
	s_cbranch_execz .LBB0_811
	v_lshlrev_b64 v[52:53], 6, v[68:69]
	v_lshl_add_u64 v[52:53], s[14:15], 0, v[52:53]
	s_waitcnt lgkmcnt(0)
	v_add_f32_e32 v50, v50, v51
	global_store_dword v[52:53], v50, off
.LBB0_811:
	s_or_b64 exec, exec, s[18:19]
	s_waitcnt vmcnt(5)
	v_cvt_f32_f16_sdwa v53, v72 dst_sel:DWORD dst_unused:UNUSED_PAD src0_sel:WORD_1
	v_cvt_f32_f16_e32 v52, v72
	v_cvt_f32_f16_sdwa v55, v73 dst_sel:DWORD dst_unused:UNUSED_PAD src0_sel:WORD_1
	v_cvt_f32_f16_e32 v54, v73
	s_waitcnt vmcnt(4)
	v_cvt_f32_f16_sdwa v57, v70 dst_sel:DWORD dst_unused:UNUSED_PAD src0_sel:WORD_1
	v_cvt_f32_f16_e32 v56, v70
	v_cvt_f32_f16_sdwa v59, v71 dst_sel:DWORD dst_unused:UNUSED_PAD src0_sel:WORD_1
	v_cvt_f32_f16_e32 v58, v71
	s_waitcnt vmcnt(3)
	v_cvt_f32_f16_sdwa v61, v64 dst_sel:DWORD dst_unused:UNUSED_PAD src0_sel:WORD_1
	v_cvt_f32_f16_e32 v60, v64
	v_cvt_f32_f16_sdwa v69, v65 dst_sel:DWORD dst_unused:UNUSED_PAD src0_sel:WORD_1
	v_cvt_f32_f16_e32 v68, v65
	s_waitcnt vmcnt(2)
	v_cvt_f32_f16_sdwa v65, v62 dst_sel:DWORD dst_unused:UNUSED_PAD src0_sel:WORD_1
	v_cvt_f32_f16_e32 v64, v62
	v_cvt_f32_f16_sdwa v71, v63 dst_sel:DWORD dst_unused:UNUSED_PAD src0_sel:WORD_1
	v_cvt_f32_f16_e32 v70, v63
	v_or_b32_e32 v62, 0x10000, v66
	v_mov_b32_e32 v63, v67
	v_lshl_add_u64 v[62:63], v[142:143], 0, v[62:63]
	v_pk_fma_f32 v[72:73], v[48:49], 0.5, v[54:55] op_sel_hi:[1,0,1]
	v_pk_fma_f32 v[74:75], v[46:47], 0.5, v[52:53] op_sel_hi:[1,0,1]
	global_load_dwordx2 v[54:55], v[62:63], off
	global_load_dwordx2 v[52:53], v[62:63], off offset:32
	global_load_dwordx2 v[48:49], v[62:63], off offset:256
	global_load_dwordx2 v[46:47], v[62:63], off offset:288
	v_cvt_f16_f32_e32 v76, v74
	v_cvt_f16_f32_sdwa v77, v75 dst_sel:WORD_1 dst_unused:UNUSED_PAD src0_sel:DWORD
	v_pk_fma_f32 v[44:45], v[44:45], 0.5, v[58:59] op_sel_hi:[1,0,1]
	v_pk_fma_f32 v[42:43], v[42:43], 0.5, v[56:57] op_sel_hi:[1,0,1]
	s_mov_b64 s[18:19], 0x90
	v_cvt_f16_f32_e32 v56, v42
	v_cvt_f16_f32_sdwa v57, v43 dst_sel:WORD_1 dst_unused:UNUSED_PAD src0_sel:DWORD
	v_cvt_f16_f32_e32 v58, v44
	v_cvt_f16_f32_sdwa v59, v45 dst_sel:WORD_1 dst_unused:UNUSED_PAD src0_sel:DWORD
	s_waitcnt lgkmcnt(0)
	v_lshl_add_u64 v[50:51], v[140:141], 0, s[18:19]
	v_cvt_f16_f32_e32 v78, v72
	v_cvt_f16_f32_sdwa v79, v73 dst_sel:WORD_1 dst_unused:UNUSED_PAD src0_sel:DWORD
	v_or_b32_e32 v62, v77, v76
	v_lshlrev_b64 v[76:77], 11, v[50:51]
	v_lshl_add_u64 v[76:77], s[16:17], 0, v[76:77]
	v_mul_f32_e32 v43, v43, v43
	v_lshl_add_u64 v[76:77], v[138:139], 1, v[76:77]
	v_or_b32_e32 v56, v57, v56
	v_or_b32_e32 v57, v59, v58
	v_fmac_f32_e32 v43, v42, v42
	v_mul_f32_e32 v42, v45, v45
	v_pk_fma_f32 v[40:41], v[40:41], 0.5, v[68:69] op_sel_hi:[1,0,1]
	v_pk_fma_f32 v[38:39], v[38:39], 0.5, v[60:61] op_sel_hi:[1,0,1]
	v_or_b32_e32 v63, v79, v78
	v_mov_b32_e32 v242, v56
	v_mov_b32_e32 v243, v57
	v_fmac_f32_e32 v42, v44, v44
	v_cvt_f16_f32_e32 v44, v38
	v_cvt_f16_f32_sdwa v45, v39 dst_sel:WORD_1 dst_unused:UNUSED_PAD src0_sel:DWORD
	v_cvt_f16_f32_e32 v56, v40
	v_cvt_f16_f32_sdwa v57, v41 dst_sel:WORD_1 dst_unused:UNUSED_PAD src0_sel:DWORD
	v_mov_b32_e32 v240, v62
	v_mov_b32_e32 v241, v63
	v_mbcnt_lo_u32_b32 v222, -1, 0
	v_mbcnt_hi_u32_b32 v222, -1, v222
	v_bfe_u32 v222, v222, 4, 1
	v_mul_u32_u24_e32 v222, 24, v222
	v_mov_b32_e32 v223, 0
	v_permlane16_swap_b32_e32 v240, v242
	v_permlane16_swap_b32_e32 v241, v243
	v_lshl_add_u64 v[222:223], v[76:77], 0, v[222:223]
	global_store_dwordx4 v[222:223], v[240:243], off sc1
	v_mul_f32_e32 v62, v75, v75
	v_mul_f32_e32 v63, v73, v73
	v_fmac_f32_e32 v62, v74, v74
	v_fmac_f32_e32 v63, v72, v72
	v_add_f32_e32 v62, v62, v63
	v_add_f32_e32 v42, v43, v42
	v_mul_f32_e32 v39, v39, v39
	v_add_f32_e32 v58, v62, v42
	v_or_b32_e32 v42, v45, v44
	v_or_b32_e32 v43, v57, v56
	v_fmac_f32_e32 v39, v38, v38
	v_mul_f32_e32 v38, v41, v41
	v_pk_fma_f32 v[36:37], v[36:37], 0.5, v[70:71] op_sel_hi:[1,0,1]
	v_pk_fma_f32 v[34:35], v[34:35], 0.5, v[64:65] op_sel_hi:[1,0,1]
	v_mov_b32_e32 v244, v42
	v_mov_b32_e32 v245, v43
	v_fmac_f32_e32 v38, v40, v40
	v_cvt_f16_f32_e32 v40, v34
	v_cvt_f16_f32_sdwa v41, v35 dst_sel:WORD_1 dst_unused:UNUSED_PAD src0_sel:DWORD
	v_cvt_f16_f32_e32 v42, v36
	v_cvt_f16_f32_sdwa v43, v37 dst_sel:WORD_1 dst_unused:UNUSED_PAD src0_sel:DWORD
	v_mul_f32_e32 v35, v35, v35
	v_fmac_f32_e32 v35, v34, v34
	v_mul_f32_e32 v34, v37, v37
	v_add_f32_e32 v38, v39, v38
	v_fmac_f32_e32 v34, v36, v36
	v_add_f32_e32 v44, v58, v38
	v_or_b32_e32 v38, v41, v40
	v_or_b32_e32 v39, v43, v42
	v_add_f32_e32 v34, v35, v34
	v_mov_b32_e32 v246, v38
	v_mov_b32_e32 v247, v39
	v_mbcnt_lo_u32_b32 v222, -1, 0
	v_mbcnt_hi_u32_b32 v222, -1, v222
	v_bfe_u32 v222, v222, 4, 1
	v_mul_u32_u24_e32 v222, 24, v222
	v_mov_b32_e32 v223, 0
	v_permlane16_swap_b32_e32 v244, v246
	v_permlane16_swap_b32_e32 v245, v247
	v_lshl_add_u64 v[222:223], v[76:77], 0, v[222:223]
	global_store_dwordx4 v[222:223], v[244:247], off offset:256 sc1
	v_add_f32_e32 v34, v44, v34
	v_mov_b32_e32 v35, v34
	s_nop 1
	v_permlane16_swap_b32_e32 v35, v34
	s_waitcnt lgkmcnt(0)
	v_add_f32_e32 v34, v34, v35
	s_nop 0
	v_mov_b32_e32 v35, v34
	s_nop 1
	v_permlane32_swap_b32_e32 v35, v34
	s_and_saveexec_b64 s[18:19], s[0:1]
	s_cbranch_execz .LBB0_813
	v_lshlrev_b64 v[36:37], 6, v[50:51]
	v_lshl_add_u64 v[36:37], s[14:15], 0, v[36:37]
	s_waitcnt lgkmcnt(0)
	v_add_f32_e32 v34, v34, v35
	global_store_dword v[36:37], v34, off
.LBB0_813:
	s_or_b64 exec, exec, s[18:19]
	s_waitcnt vmcnt(5)
	v_cvt_f32_f16_sdwa v37, v54 dst_sel:DWORD dst_unused:UNUSED_PAD src0_sel:WORD_1
	v_cvt_f32_f16_e32 v36, v54
	v_cvt_f32_f16_sdwa v39, v55 dst_sel:DWORD dst_unused:UNUSED_PAD src0_sel:WORD_1
	v_cvt_f32_f16_e32 v38, v55
	v_or_b32_e32 v66, 0x18000, v66
	s_waitcnt vmcnt(4)
	v_cvt_f32_f16_sdwa v41, v52 dst_sel:DWORD dst_unused:UNUSED_PAD src0_sel:WORD_1
	v_cvt_f32_f16_e32 v40, v52
	v_cvt_f32_f16_sdwa v43, v53 dst_sel:DWORD dst_unused:UNUSED_PAD src0_sel:WORD_1
	v_cvt_f32_f16_e32 v42, v53
	s_waitcnt vmcnt(3)
	v_cvt_f32_f16_sdwa v45, v48 dst_sel:DWORD dst_unused:UNUSED_PAD src0_sel:WORD_1
	v_cvt_f32_f16_e32 v44, v48
	v_cvt_f32_f16_sdwa v51, v49 dst_sel:DWORD dst_unused:UNUSED_PAD src0_sel:WORD_1
	v_cvt_f32_f16_e32 v50, v49
	s_waitcnt vmcnt(2)
	v_cvt_f32_f16_sdwa v49, v46 dst_sel:DWORD dst_unused:UNUSED_PAD src0_sel:WORD_1
	v_cvt_f32_f16_e32 v48, v46
	v_cvt_f32_f16_sdwa v53, v47 dst_sel:DWORD dst_unused:UNUSED_PAD src0_sel:WORD_1
	v_cvt_f32_f16_e32 v52, v47
	v_lshl_add_u64 v[46:47], v[142:143], 0, v[66:67]
	v_pk_fma_f32 v[54:55], v[32:33], 0.5, v[38:39] op_sel_hi:[1,0,1]
	v_pk_fma_f32 v[56:57], v[30:31], 0.5, v[36:37] op_sel_hi:[1,0,1]
	global_load_dwordx2 v[38:39], v[46:47], off
	global_load_dwordx2 v[36:37], v[46:47], off offset:32
	global_load_dwordx2 v[32:33], v[46:47], off offset:256
	global_load_dwordx2 v[30:31], v[46:47], off offset:288
	v_cvt_f16_f32_e32 v58, v56
	v_cvt_f16_f32_sdwa v59, v57 dst_sel:WORD_1 dst_unused:UNUSED_PAD src0_sel:DWORD
	v_pk_fma_f32 v[28:29], v[28:29], 0.5, v[42:43] op_sel_hi:[1,0,1]
	v_pk_fma_f32 v[26:27], v[26:27], 0.5, v[40:41] op_sel_hi:[1,0,1]
	s_mov_b64 s[18:19], 0xa0
	v_cvt_f16_f32_e32 v40, v26
	v_cvt_f16_f32_sdwa v41, v27 dst_sel:WORD_1 dst_unused:UNUSED_PAD src0_sel:DWORD
	v_cvt_f16_f32_e32 v42, v28
	v_cvt_f16_f32_sdwa v43, v29 dst_sel:WORD_1 dst_unused:UNUSED_PAD src0_sel:DWORD
	s_waitcnt lgkmcnt(0)
	v_lshl_add_u64 v[34:35], v[140:141], 0, s[18:19]
	v_cvt_f16_f32_e32 v60, v54
	v_cvt_f16_f32_sdwa v61, v55 dst_sel:WORD_1 dst_unused:UNUSED_PAD src0_sel:DWORD
	v_or_b32_e32 v46, v59, v58
	v_lshlrev_b64 v[58:59], 11, v[34:35]
	v_lshl_add_u64 v[58:59], s[16:17], 0, v[58:59]
	v_mul_f32_e32 v27, v27, v27
	v_lshl_add_u64 v[58:59], v[138:139], 1, v[58:59]
	v_or_b32_e32 v40, v41, v40
	v_or_b32_e32 v41, v43, v42
	v_fmac_f32_e32 v27, v26, v26
	v_mul_f32_e32 v26, v29, v29
	v_pk_fma_f32 v[24:25], v[24:25], 0.5, v[50:51] op_sel_hi:[1,0,1]
	v_pk_fma_f32 v[22:23], v[22:23], 0.5, v[44:45] op_sel_hi:[1,0,1]
	v_or_b32_e32 v47, v61, v60
	v_mov_b32_e32 v242, v40
	v_mov_b32_e32 v243, v41
	v_fmac_f32_e32 v26, v28, v28
	v_cvt_f16_f32_e32 v28, v22
	v_cvt_f16_f32_sdwa v29, v23 dst_sel:WORD_1 dst_unused:UNUSED_PAD src0_sel:DWORD
	v_cvt_f16_f32_e32 v40, v24
	v_cvt_f16_f32_sdwa v41, v25 dst_sel:WORD_1 dst_unused:UNUSED_PAD src0_sel:DWORD
	v_mov_b32_e32 v240, v46
	v_mov_b32_e32 v241, v47
	v_mbcnt_lo_u32_b32 v222, -1, 0
	v_mbcnt_hi_u32_b32 v222, -1, v222
	v_bfe_u32 v222, v222, 4, 1
	v_mul_u32_u24_e32 v222, 24, v222
	v_mov_b32_e32 v223, 0
	v_permlane16_swap_b32_e32 v240, v242
	v_permlane16_swap_b32_e32 v241, v243
	v_lshl_add_u64 v[222:223], v[58:59], 0, v[222:223]
	global_store_dwordx4 v[222:223], v[240:243], off sc1
	v_mul_f32_e32 v46, v57, v57
	v_mul_f32_e32 v47, v55, v55
	v_fmac_f32_e32 v46, v56, v56
	v_fmac_f32_e32 v47, v54, v54
	v_add_f32_e32 v46, v46, v47
	v_add_f32_e32 v26, v27, v26
	v_mul_f32_e32 v23, v23, v23
	v_add_f32_e32 v42, v46, v26
	v_or_b32_e32 v26, v29, v28
	v_or_b32_e32 v27, v41, v40
	v_fmac_f32_e32 v23, v22, v22
	v_mul_f32_e32 v22, v25, v25
	v_pk_fma_f32 v[20:21], v[20:21], 0.5, v[52:53] op_sel_hi:[1,0,1]
	v_pk_fma_f32 v[18:19], v[18:19], 0.5, v[48:49] op_sel_hi:[1,0,1]
	v_mov_b32_e32 v244, v26
	v_mov_b32_e32 v245, v27
	v_fmac_f32_e32 v22, v24, v24
	v_cvt_f16_f32_e32 v24, v18
	v_cvt_f16_f32_sdwa v25, v19 dst_sel:WORD_1 dst_unused:UNUSED_PAD src0_sel:DWORD
	v_cvt_f16_f32_e32 v26, v20
	v_cvt_f16_f32_sdwa v27, v21 dst_sel:WORD_1 dst_unused:UNUSED_PAD src0_sel:DWORD
	v_mul_f32_e32 v19, v19, v19
	v_fmac_f32_e32 v19, v18, v18
	v_mul_f32_e32 v18, v21, v21
	v_add_f32_e32 v22, v23, v22
	v_fmac_f32_e32 v18, v20, v20
	v_add_f32_e32 v28, v42, v22
	v_or_b32_e32 v22, v25, v24
	v_or_b32_e32 v23, v27, v26
	v_add_f32_e32 v18, v19, v18
	v_mov_b32_e32 v246, v22
	v_mov_b32_e32 v247, v23
	v_mbcnt_lo_u32_b32 v222, -1, 0
	v_mbcnt_hi_u32_b32 v222, -1, v222
	v_bfe_u32 v222, v222, 4, 1
	v_mul_u32_u24_e32 v222, 24, v222
	v_mov_b32_e32 v223, 0
	v_permlane16_swap_b32_e32 v244, v246
	v_permlane16_swap_b32_e32 v245, v247
	v_lshl_add_u64 v[222:223], v[58:59], 0, v[222:223]
	global_store_dwordx4 v[222:223], v[244:247], off offset:256 sc1
	v_add_f32_e32 v18, v28, v18
	v_mov_b32_e32 v19, v18
	s_nop 1
	v_permlane16_swap_b32_e32 v19, v18
	s_waitcnt lgkmcnt(0)
	v_add_f32_e32 v18, v18, v19
	s_nop 0
	v_mov_b32_e32 v19, v18
	s_nop 1
	v_permlane32_swap_b32_e32 v19, v18
	s_and_saveexec_b64 s[18:19], s[0:1]
	s_cbranch_execz .LBB0_815
	v_lshlrev_b64 v[20:21], 6, v[34:35]
	v_lshl_add_u64 v[20:21], s[14:15], 0, v[20:21]
	s_waitcnt lgkmcnt(0)
	v_add_f32_e32 v18, v18, v19
	global_store_dword v[20:21], v18, off
.LBB0_815:
	s_or_b64 exec, exec, s[18:19]
	s_waitcnt vmcnt(5)
	v_cvt_f32_f16_sdwa v21, v38 dst_sel:DWORD dst_unused:UNUSED_PAD src0_sel:WORD_1
	v_cvt_f32_f16_e32 v20, v38
	v_cvt_f32_f16_sdwa v23, v39 dst_sel:DWORD dst_unused:UNUSED_PAD src0_sel:WORD_1
	v_cvt_f32_f16_e32 v22, v39
	s_waitcnt vmcnt(4)
	v_cvt_f32_f16_sdwa v25, v36 dst_sel:DWORD dst_unused:UNUSED_PAD src0_sel:WORD_1
	v_cvt_f32_f16_e32 v24, v36
	v_pk_fma_f32 v[14:15], v[14:15], 0.5, v[20:21] op_sel_hi:[1,0,1]
	v_cvt_f32_f16_sdwa v27, v37 dst_sel:DWORD dst_unused:UNUSED_PAD src0_sel:WORD_1
	v_cvt_f32_f16_e32 v26, v37
	v_cvt_f16_f32_e32 v20, v14
	v_cvt_f16_f32_sdwa v21, v15 dst_sel:WORD_1 dst_unused:UNUSED_PAD src0_sel:DWORD
	v_pk_fma_f32 v[16:17], v[16:17], 0.5, v[22:23] op_sel_hi:[1,0,1]
	v_mul_f32_e32 v15, v15, v15
	v_fmac_f32_e32 v15, v14, v14
	v_mul_f32_e32 v14, v17, v17
	s_waitcnt vmcnt(3)
	v_cvt_f32_f16_sdwa v29, v32 dst_sel:DWORD dst_unused:UNUSED_PAD src0_sel:WORD_1
	v_cvt_f32_f16_e32 v28, v32
	v_fmac_f32_e32 v14, v16, v16
	v_pk_fma_f32 v[10:11], v[10:11], 0.5, v[24:25] op_sel_hi:[1,0,1]
	v_cvt_f32_f16_sdwa v35, v33 dst_sel:DWORD dst_unused:UNUSED_PAD src0_sel:WORD_1
	v_cvt_f32_f16_e32 v34, v33
	v_or_b32_e32 v20, v21, v20
	v_cvt_f16_f32_e32 v21, v16
	v_add_f32_e32 v16, v15, v14
	v_pk_fma_f32 v[12:13], v[12:13], 0.5, v[26:27] op_sel_hi:[1,0,1]
	v_cvt_f16_f32_e32 v14, v10
	v_cvt_f16_f32_sdwa v15, v11 dst_sel:WORD_1 dst_unused:UNUSED_PAD src0_sel:DWORD
	v_mul_f32_e32 v11, v11, v11
	v_fmac_f32_e32 v11, v10, v10
	v_mul_f32_e32 v10, v13, v13
	v_fmac_f32_e32 v10, v12, v12
	s_waitcnt vmcnt(2)
	v_cvt_f32_f16_sdwa v33, v30 dst_sel:DWORD dst_unused:UNUSED_PAD src0_sel:WORD_1
	v_cvt_f32_f16_e32 v32, v30
	v_add_f32_e32 v10, v11, v10
	v_pk_fma_f32 v[6:7], v[6:7], 0.5, v[28:29] op_sel_hi:[1,0,1]
	v_or_b32_e32 v14, v15, v14
	v_cvt_f16_f32_e32 v15, v12
	v_add_f32_e32 v12, v16, v10
	v_pk_fma_f32 v[8:9], v[8:9], 0.5, v[34:35] op_sel_hi:[1,0,1]
	v_cvt_f16_f32_e32 v10, v6
	v_cvt_f16_f32_sdwa v11, v7 dst_sel:WORD_1 dst_unused:UNUSED_PAD src0_sel:DWORD
	v_mul_f32_e32 v7, v7, v7
	v_fmac_f32_e32 v7, v6, v6
	v_mul_f32_e32 v6, v9, v9
	v_fmac_f32_e32 v6, v8, v8
	v_cvt_f32_f16_sdwa v37, v31 dst_sel:DWORD dst_unused:UNUSED_PAD src0_sel:WORD_1
	v_cvt_f32_f16_e32 v36, v31
	v_add_f32_e32 v6, v7, v6
	v_pk_fma_f32 v[2:3], v[2:3], 0.5, v[32:33] op_sel_hi:[1,0,1]
	v_or_b32_e32 v10, v11, v10
	v_cvt_f16_f32_e32 v11, v8
	v_add_f32_e32 v8, v12, v6
	v_cvt_f16_f32_e32 v6, v2
	v_cvt_f16_f32_sdwa v7, v3 dst_sel:WORD_1 dst_unused:UNUSED_PAD src0_sel:DWORD
	v_cvt_f16_f32_sdwa v22, v17 dst_sel:WORD_1 dst_unused:UNUSED_PAD src0_sel:DWORD
	v_pk_fma_f32 v[4:5], v[4:5], 0.5, v[36:37] op_sel_hi:[1,0,1]
	s_mov_b64 s[18:19], 0xb0
	v_cvt_f16_f32_sdwa v17, v13 dst_sel:WORD_1 dst_unused:UNUSED_PAD src0_sel:DWORD
	v_cvt_f16_f32_sdwa v13, v9 dst_sel:WORD_1 dst_unused:UNUSED_PAD src0_sel:DWORD
	v_or_b32_e32 v6, v7, v6
	v_cvt_f16_f32_e32 v7, v4
	v_cvt_f16_f32_sdwa v9, v5 dst_sel:WORD_1 dst_unused:UNUSED_PAD src0_sel:DWORD
	s_waitcnt lgkmcnt(0)
	v_lshl_add_u64 v[18:19], v[140:141], 0, s[18:19]
	v_mul_f32_e32 v3, v3, v3
	v_or_b32_e32 v21, v22, v21
	v_lshlrev_b64 v[22:23], 11, v[18:19]
	v_fmac_f32_e32 v3, v2, v2
	v_mul_f32_e32 v2, v5, v5
	v_lshl_add_u64 v[22:23], s[16:17], 0, v[22:23]
	v_fmac_f32_e32 v2, v4, v4
	v_lshl_add_u64 v[22:23], v[138:139], 1, v[22:23]
	v_or_b32_e32 v15, v17, v15
	v_or_b32_e32 v11, v13, v11
	v_or_b32_e32 v7, v9, v7
	v_add_f32_e32 v2, v3, v2
	v_mov_b32_e32 v240, v20
	v_mov_b32_e32 v241, v21
	v_mov_b32_e32 v242, v14
	v_mov_b32_e32 v243, v15
	v_mbcnt_lo_u32_b32 v222, -1, 0
	v_mbcnt_hi_u32_b32 v222, -1, v222
	v_bfe_u32 v222, v222, 4, 1
	v_mul_u32_u24_e32 v222, 24, v222
	v_mov_b32_e32 v223, 0
	v_permlane16_swap_b32_e32 v240, v242
	v_permlane16_swap_b32_e32 v241, v243
	v_lshl_add_u64 v[222:223], v[22:23], 0, v[222:223]
	global_store_dwordx4 v[222:223], v[240:243], off sc1
	v_mov_b32_e32 v244, v10
	v_mov_b32_e32 v245, v11
	v_mov_b32_e32 v246, v6
	v_mov_b32_e32 v247, v7
	v_mbcnt_lo_u32_b32 v222, -1, 0
	v_mbcnt_hi_u32_b32 v222, -1, v222
	v_bfe_u32 v222, v222, 4, 1
	v_mul_u32_u24_e32 v222, 24, v222
	v_mov_b32_e32 v223, 0
	v_permlane16_swap_b32_e32 v244, v246
	v_permlane16_swap_b32_e32 v245, v247
	v_lshl_add_u64 v[222:223], v[22:23], 0, v[222:223]
	global_store_dwordx4 v[222:223], v[244:247], off offset:256 sc1
	v_add_f32_e32 v2, v8, v2
	v_mov_b32_e32 v3, v2
	s_nop 1
	v_permlane16_swap_b32_e32 v3, v2
	s_waitcnt lgkmcnt(0)
	v_add_f32_e32 v2, v2, v3
	s_nop 0
	v_mov_b32_e32 v3, v2
	s_nop 1
	v_permlane32_swap_b32_e32 v3, v2
	s_and_saveexec_b64 s[16:17], s[0:1]
	s_cbranch_execz .LBB0_817
	v_lshlrev_b64 v[4:5], 6, v[18:19]
	v_lshl_add_u64 v[4:5], s[14:15], 0, v[4:5]
	s_waitcnt lgkmcnt(0)
	v_add_f32_e32 v2, v2, v3
	global_store_dword v[4:5], v2, off

.LBB0_1990:
	s_ashr_i32 s23, s22, 31
	s_lshl_b64 s[22:23], s[22:23], 8
	v_lshl_or_b32 v138, s20, 8, v155
	v_lshl_add_u64 v[140:141], s[22:23], 0, v[132:133]
	s_mov_b32 s13, s33
	v_ashrrev_i32_e32 v139, 31, v138
	v_lshlrev_b64 v[146:147], 11, v[140:141]
	v_lshl_add_u64 v[142:143], s[26:27], 0, v[146:147]
	v_lshlrev_b64 v[148:149], 1, v[138:139]
	s_mov_b32 s13, s33
	v_lshl_add_u64 v[142:143], v[142:143], 0, v[148:149]
	global_load_dwordx2 v[158:159], v[142:143], off
	global_load_dwordx2 v[160:161], v[142:143], off offset:32
	global_load_dwordx2 v[162:163], v[142:143], off offset:256
	global_load_dwordx2 v[164:165], v[142:143], off offset:288
	v_mov_b32_e32 v142, s13
	ds_read2_b32 v[166:167], v142 offset1:1
	v_lshl_add_u64 v[142:143], s[26:27], 0, v[148:149]
	v_lshl_add_u64 v[144:145], v[142:143], 0, v[146:147]
	v_add_co_u32_e32 v168, vcc, s54, v144
	v_lshl_add_u64 v[146:147], s[24:25], 0, v[146:147]
	s_nop 0
	v_addc_co_u32_e32 v169, vcc, 0, v145, vcc
	v_lshl_add_u64 v[170:171], v[146:147], 0, v[148:149]
	global_load_dwordx2 v[152:153], v[168:169], off
	global_load_dwordx2 v[150:151], v[168:169], off offset:32
	global_load_dwordx2 v[148:149], v[168:169], off offset:256
	global_load_dwordx2 v[146:147], v[168:169], off offset:288
	s_waitcnt lgkmcnt(0)
	v_readfirstlane_b32 s13, v166
	v_readfirstlane_b32 s15, v167
	s_lshl_b32 s20, s20, 2
	s_ashr_i32 s21, s20, 31
	s_lshl_b64 s[20:21], s[20:21], 2
	s_add_u32 s13, s13, s20
	s_addc_u32 s15, s15, s21
	s_add_u32 s13, s13, s48
	s_addc_u32 s15, s15, 0
	s_add_u32 s20, s13, 0x10380000
	s_addc_u32 s21, s15, 0
	s_waitcnt vmcnt(0)
	v_cvt_f32_f16_e32 v166, v158
	v_cvt_f32_f16_sdwa v167, v158 dst_sel:DWORD dst_unused:UNUSED_PAD src0_sel:WORD_1
	v_cvt_f32_f16_e32 v158, v159
	v_cvt_f32_f16_sdwa v159, v159 dst_sel:DWORD dst_unused:UNUSED_PAD src0_sel:WORD_1
	v_cvt_f32_f16_e32 v168, v160
	v_cvt_f32_f16_sdwa v169, v160 dst_sel:DWORD dst_unused:UNUSED_PAD src0_sel:WORD_1
	v_cvt_f32_f16_e32 v160, v161
	v_cvt_f32_f16_sdwa v161, v161 dst_sel:DWORD dst_unused:UNUSED_PAD src0_sel:WORD_1
	v_cvt_f32_f16_e32 v172, v162
	v_cvt_f32_f16_sdwa v173, v162 dst_sel:DWORD dst_unused:UNUSED_PAD src0_sel:WORD_1
	v_cvt_f32_f16_e32 v162, v163
	v_cvt_f32_f16_sdwa v163, v163 dst_sel:DWORD dst_unused:UNUSED_PAD src0_sel:WORD_1
	v_cvt_f32_f16_e32 v174, v164
	v_cvt_f32_f16_sdwa v175, v164 dst_sel:DWORD dst_unused:UNUSED_PAD src0_sel:WORD_1
	v_cvt_f32_f16_e32 v164, v165
	v_cvt_f32_f16_sdwa v165, v165 dst_sel:DWORD dst_unused:UNUSED_PAD src0_sel:WORD_1
	v_pk_add_f32 v[128:129], v[128:129], v[158:159]
	v_pk_add_f32 v[126:127], v[126:127], v[166:167]
	v_pk_add_f32 v[124:125], v[124:125], v[160:161]
	v_pk_add_f32 v[122:123], v[122:123], v[168:169]
	v_pk_add_f32 v[120:121], v[120:121], v[162:163]
	v_pk_add_f32 v[118:119], v[118:119], v[172:173]
	v_cvt_f16_f32_e32 v157, v126
	v_cvt_f16_f32_sdwa v158, v127 dst_sel:WORD_1 dst_unused:UNUSED_PAD src0_sel:DWORD
	v_cvt_f16_f32_e32 v159, v128
	v_cvt_f16_f32_sdwa v160, v129 dst_sel:WORD_1 dst_unused:UNUSED_PAD src0_sel:DWORD
	v_pk_add_f32 v[116:117], v[116:117], v[164:165]
	v_mul_f32_e32 v127, v127, v127
	v_mul_f32_e32 v129, v129, v129
	v_cvt_f16_f32_e32 v161, v122
	v_cvt_f16_f32_sdwa v162, v123 dst_sel:WORD_1 dst_unused:UNUSED_PAD src0_sel:DWORD
	v_cvt_f16_f32_e32 v163, v124
	v_cvt_f16_f32_sdwa v164, v125 dst_sel:WORD_1 dst_unused:UNUSED_PAD src0_sel:DWORD
	v_mul_f32_e32 v123, v123, v123
	v_mul_f32_e32 v125, v125, v125
	v_cvt_f16_f32_e32 v165, v118
	v_cvt_f16_f32_sdwa v166, v119 dst_sel:WORD_1 dst_unused:UNUSED_PAD src0_sel:DWORD
	v_cvt_f16_f32_e32 v167, v120
	v_cvt_f16_f32_sdwa v168, v121 dst_sel:WORD_1 dst_unused:UNUSED_PAD src0_sel:DWORD
	v_mul_f32_e32 v169, v119, v119
	v_fmac_f32_e32 v127, v126, v126
	v_fmac_f32_e32 v129, v128, v128
	v_fmac_f32_e32 v123, v122, v122
	v_fmac_f32_e32 v125, v124, v124
	v_fmac_f32_e32 v169, v118, v118
	v_add_f32_e32 v118, v127, v129
	v_add_f32_e32 v119, v123, v125
	v_pk_add_f32 v[114:115], v[114:115], v[174:175]
	v_mul_f32_e32 v172, v121, v121
	v_add_f32_e32 v124, v118, v119
	v_or_b32_e32 v118, v158, v157
	v_or_b32_e32 v119, v160, v159
	v_cvt_f16_f32_e32 v173, v114
	v_cvt_f16_f32_sdwa v174, v115 dst_sel:WORD_1 dst_unused:UNUSED_PAD src0_sel:DWORD
	v_cvt_f16_f32_e32 v175, v116
	v_fmac_f32_e32 v172, v120, v120
	v_or_b32_e32 v120, v162, v161
	v_or_b32_e32 v121, v164, v163
	v_or_b32_e32 v122, v166, v165
	v_or_b32_e32 v123, v168, v167
	v_mov_b32_e32 v240, v118
	v_mov_b32_e32 v241, v119
	v_mov_b32_e32 v242, v120
	v_mov_b32_e32 v243, v121
	v_mbcnt_lo_u32_b32 v222, -1, 0
	v_mbcnt_hi_u32_b32 v222, -1, v222
	v_bfe_u32 v222, v222, 4, 1
	v_mul_u32_u24_e32 v222, 24, v222
	v_mov_b32_e32 v223, 0
	v_permlane16_swap_b32_e32 v240, v242
	v_permlane16_swap_b32_e32 v241, v243
	v_lshl_add_u64 v[222:223], v[170:171], 0, v[222:223]
	global_store_dwordx4 v[222:223], v[240:243], off sc1
	v_mov_b32_e32 v244, v122
	v_mov_b32_e32 v245, v123
	v_cvt_f16_f32_sdwa v119, v117 dst_sel:WORD_1 dst_unused:UNUSED_PAD src0_sel:DWORD
	v_mul_f32_e32 v115, v115, v115
	v_fmac_f32_e32 v115, v114, v114
	v_mul_f32_e32 v114, v117, v117
	v_add_f32_e32 v118, v169, v172
	v_fmac_f32_e32 v114, v116, v116
	v_add_f32_e32 v120, v124, v118
	v_or_b32_e32 v118, v174, v173
	v_or_b32_e32 v119, v119, v175
	v_add_f32_e32 v114, v115, v114
	v_mov_b32_e32 v246, v118
	v_mov_b32_e32 v247, v119
	v_mbcnt_lo_u32_b32 v222, -1, 0
	v_mbcnt_hi_u32_b32 v222, -1, v222
	v_bfe_u32 v222, v222, 4, 1
	v_mul_u32_u24_e32 v222, 24, v222
	v_mov_b32_e32 v223, 0
	v_permlane16_swap_b32_e32 v244, v246
	v_permlane16_swap_b32_e32 v245, v247
	v_lshl_add_u64 v[222:223], v[170:171], 0, v[222:223]
	global_store_dwordx4 v[222:223], v[244:247], off offset:256 sc1
	v_add_f32_e32 v114, v120, v114
	v_mov_b32_e32 v115, v114
	s_nop 1
	v_permlane16_swap_b32_e32 v115, v114
	s_waitcnt lgkmcnt(0)
	v_add_f32_e32 v114, v114, v115
	s_nop 0
	v_mov_b32_e32 v115, v114
	s_nop 1
	v_permlane32_swap_b32_e32 v115, v114
	s_and_saveexec_b64 s[22:23], s[0:1]
	s_cbranch_execz .LBB0_1992
	v_lshlrev_b64 v[116:117], 6, v[140:141]
	v_lshl_add_u64 v[116:117], s[20:21], 0, v[116:117]
	s_waitcnt lgkmcnt(0)
	v_add_f32_e32 v114, v114, v115
	global_store_dword v[116:117], v114, off
.LBB0_1992:
	s_or_b64 exec, exec, s[22:23]
	v_cvt_f32_f16_sdwa v117, v152 dst_sel:DWORD dst_unused:UNUSED_PAD src0_sel:WORD_1
	v_cvt_f32_f16_e32 v116, v152
	v_cvt_f32_f16_sdwa v119, v153 dst_sel:DWORD dst_unused:UNUSED_PAD src0_sel:WORD_1
	v_cvt_f32_f16_e32 v118, v153
	s_mov_b32 s13, 0x10000
	v_cvt_f32_f16_sdwa v129, v146 dst_sel:DWORD dst_unused:UNUSED_PAD src0_sel:WORD_1
	v_cvt_f32_f16_e32 v128, v146
	v_add_co_u32_e32 v146, vcc, s13, v144
	v_cvt_f32_f16_sdwa v125, v148 dst_sel:DWORD dst_unused:UNUSED_PAD src0_sel:WORD_1
	v_cvt_f32_f16_e32 v124, v148
	v_cvt_f32_f16_sdwa v127, v149 dst_sel:DWORD dst_unused:UNUSED_PAD src0_sel:WORD_1
	v_cvt_f32_f16_e32 v126, v149
	v_cvt_f32_f16_sdwa v149, v147 dst_sel:DWORD dst_unused:UNUSED_PAD src0_sel:WORD_1
	v_cvt_f32_f16_e32 v148, v147
	v_addc_co_u32_e32 v147, vcc, 0, v145, vcc
	v_cvt_f32_f16_sdwa v121, v150 dst_sel:DWORD dst_unused:UNUSED_PAD src0_sel:WORD_1
	v_cvt_f32_f16_e32 v120, v150
	v_cvt_f32_f16_sdwa v123, v151 dst_sel:DWORD dst_unused:UNUSED_PAD src0_sel:WORD_1
	v_cvt_f32_f16_e32 v122, v151
	v_pk_add_f32 v[150:151], v[112:113], v[118:119]
	v_pk_add_f32 v[152:153], v[110:111], v[116:117]
	global_load_dwordx2 v[118:119], v[146:147], off
	global_load_dwordx2 v[116:117], v[146:147], off offset:32
	global_load_dwordx2 v[112:113], v[146:147], off offset:256
	global_load_dwordx2 v[110:111], v[146:147], off offset:288
	v_cvt_f16_f32_e32 v157, v152
	v_cvt_f16_f32_sdwa v158, v153 dst_sel:WORD_1 dst_unused:UNUSED_PAD src0_sel:DWORD
	v_cvt_f16_f32_e32 v159, v150
	v_cvt_f16_f32_sdwa v160, v151 dst_sel:WORD_1 dst_unused:UNUSED_PAD src0_sel:DWORD
	v_pk_add_f32 v[108:109], v[108:109], v[122:123]
	v_pk_add_f32 v[106:107], v[106:107], v[120:121]
	v_cvt_f16_f32_e32 v122, v108
	v_cvt_f16_f32_e32 v120, v106
	v_cvt_f16_f32_sdwa v121, v107 dst_sel:WORD_1 dst_unused:UNUSED_PAD src0_sel:DWORD
	v_cvt_f16_f32_sdwa v123, v109 dst_sel:WORD_1 dst_unused:UNUSED_PAD src0_sel:DWORD
	v_or_b32_e32 v114, 16, v140
	s_waitcnt lgkmcnt(0)
	v_mov_b32_e32 v115, v141
	v_or_b32_e32 v146, v158, v157
	v_or_b32_e32 v147, v160, v159
	v_lshlrev_b64 v[158:159], 11, v[114:115]
	v_lshl_add_u64 v[158:159], s[24:25], 0, v[158:159]
	v_mul_f32_e32 v107, v107, v107
	v_lshl_add_u64 v[158:159], v[138:139], 1, v[158:159]
	v_or_b32_e32 v120, v121, v120
	v_or_b32_e32 v121, v123, v122
	v_fmac_f32_e32 v107, v106, v106
	v_mul_f32_e32 v106, v109, v109
	v_pk_add_f32 v[104:105], v[104:105], v[126:127]
	v_pk_add_f32 v[102:103], v[102:103], v[124:125]
	v_mov_b32_e32 v242, v120
	v_mov_b32_e32 v243, v121
	v_fmac_f32_e32 v106, v108, v108
	v_cvt_f16_f32_e32 v108, v102
	v_cvt_f16_f32_sdwa v109, v103 dst_sel:WORD_1 dst_unused:UNUSED_PAD src0_sel:DWORD
	v_cvt_f16_f32_e32 v120, v104
	v_cvt_f16_f32_sdwa v121, v105 dst_sel:WORD_1 dst_unused:UNUSED_PAD src0_sel:DWORD
	v_mov_b32_e32 v240, v146
	v_mov_b32_e32 v241, v147
	v_mbcnt_lo_u32_b32 v222, -1, 0
	v_mbcnt_hi_u32_b32 v222, -1, v222
	v_bfe_u32 v222, v222, 4, 1
	v_mul_u32_u24_e32 v222, 24, v222
	v_mov_b32_e32 v223, 0
	v_permlane16_swap_b32_e32 v240, v242
	v_permlane16_swap_b32_e32 v241, v243
	v_lshl_add_u64 v[222:223], v[158:159], 0, v[222:223]
	global_store_dwordx4 v[222:223], v[240:243], off sc1
	v_mul_f32_e32 v146, v153, v153
	v_mul_f32_e32 v147, v151, v151
	v_fmac_f32_e32 v146, v152, v152
	v_fmac_f32_e32 v147, v150, v150
	v_add_f32_e32 v146, v146, v147
	v_add_f32_e32 v106, v107, v106
	v_mul_f32_e32 v103, v103, v103
	v_add_f32_e32 v122, v146, v106
	v_or_b32_e32 v106, v109, v108
	v_or_b32_e32 v107, v121, v120
	v_fmac_f32_e32 v103, v102, v102
	v_mul_f32_e32 v102, v105, v105
	v_pk_add_f32 v[100:101], v[100:101], v[148:149]
	v_pk_add_f32 v[98:99], v[98:99], v[128:129]
	v_mov_b32_e32 v244, v106
	v_mov_b32_e32 v245, v107
	v_fmac_f32_e32 v102, v104, v104
	v_cvt_f16_f32_e32 v104, v98
	v_cvt_f16_f32_sdwa v105, v99 dst_sel:WORD_1 dst_unused:UNUSED_PAD src0_sel:DWORD
	v_cvt_f16_f32_e32 v106, v100
	v_cvt_f16_f32_sdwa v107, v101 dst_sel:WORD_1 dst_unused:UNUSED_PAD src0_sel:DWORD
	v_mul_f32_e32 v99, v99, v99
	v_fmac_f32_e32 v99, v98, v98
	v_mul_f32_e32 v98, v101, v101
	v_add_f32_e32 v102, v103, v102
	v_fmac_f32_e32 v98, v100, v100
	v_add_f32_e32 v108, v122, v102
	v_or_b32_e32 v102, v105, v104
	v_or_b32_e32 v103, v107, v106
	v_add_f32_e32 v98, v99, v98
	v_mov_b32_e32 v246, v102
	v_mov_b32_e32 v247, v103
	v_mbcnt_lo_u32_b32 v222, -1, 0
	v_mbcnt_hi_u32_b32 v222, -1, v222
	v_bfe_u32 v222, v222, 4, 1
	v_mul_u32_u24_e32 v222, 24, v222
	v_mov_b32_e32 v223, 0
	v_permlane16_swap_b32_e32 v244, v246
	v_permlane16_swap_b32_e32 v245, v247
	v_lshl_add_u64 v[222:223], v[158:159], 0, v[222:223]
	global_store_dwordx4 v[222:223], v[244:247], off offset:256 sc1
	v_add_f32_e32 v98, v108, v98
	v_mov_b32_e32 v99, v98
	s_nop 1
	v_permlane16_swap_b32_e32 v99, v98
	s_waitcnt lgkmcnt(0)
	v_add_f32_e32 v98, v98, v99
	s_nop 0
	v_mov_b32_e32 v99, v98
	s_nop 1
	v_permlane32_swap_b32_e32 v99, v98
	s_and_saveexec_b64 s[22:23], s[0:1]
	s_movk_i32 s53, 0x5ff
	s_cbranch_execz .LBB0_1994
	v_lshlrev_b64 v[100:101], 6, v[114:115]
	v_lshl_add_u64 v[100:101], s[20:21], 0, v[100:101]
	s_waitcnt lgkmcnt(0)
	v_add_f32_e32 v98, v98, v99
	global_store_dword v[100:101], v98, off
.LBB0_1994:
	s_or_b64 exec, exec, s[22:23]
	s_waitcnt vmcnt(5)
	v_cvt_f32_f16_sdwa v101, v118 dst_sel:DWORD dst_unused:UNUSED_PAD src0_sel:WORD_1
	v_cvt_f32_f16_e32 v100, v118
	v_cvt_f32_f16_sdwa v103, v119 dst_sel:DWORD dst_unused:UNUSED_PAD src0_sel:WORD_1
	v_cvt_f32_f16_e32 v102, v119
	s_mov_b32 s13, 0x18000
	s_waitcnt vmcnt(3)
	v_cvt_f32_f16_sdwa v109, v112 dst_sel:DWORD dst_unused:UNUSED_PAD src0_sel:WORD_1
	v_cvt_f32_f16_e32 v108, v112
	v_cvt_f32_f16_sdwa v115, v113 dst_sel:DWORD dst_unused:UNUSED_PAD src0_sel:WORD_1
	v_cvt_f32_f16_e32 v114, v113
	s_waitcnt vmcnt(2)
	v_cvt_f32_f16_sdwa v113, v110 dst_sel:DWORD dst_unused:UNUSED_PAD src0_sel:WORD_1
	v_cvt_f32_f16_e32 v112, v110
	v_add_co_u32_e32 v110, vcc, s13, v144
	v_cvt_f32_f16_sdwa v105, v116 dst_sel:DWORD dst_unused:UNUSED_PAD src0_sel:WORD_1
	v_cvt_f32_f16_e32 v104, v116
	v_cvt_f32_f16_sdwa v107, v117 dst_sel:DWORD dst_unused:UNUSED_PAD src0_sel:WORD_1
	v_cvt_f32_f16_e32 v106, v117
	v_cvt_f32_f16_sdwa v117, v111 dst_sel:DWORD dst_unused:UNUSED_PAD src0_sel:WORD_1
	v_cvt_f32_f16_e32 v116, v111
	v_addc_co_u32_e32 v111, vcc, 0, v145, vcc
	v_pk_add_f32 v[118:119], v[96:97], v[102:103]
	v_pk_add_f32 v[120:121], v[94:95], v[100:101]
	global_load_dwordx2 v[102:103], v[110:111], off
	global_load_dwordx2 v[100:101], v[110:111], off offset:32
	global_load_dwordx2 v[96:97], v[110:111], off offset:256
	global_load_dwordx2 v[94:95], v[110:111], off offset:288
	v_cvt_f16_f32_e32 v122, v120
	v_cvt_f16_f32_sdwa v123, v121 dst_sel:WORD_1 dst_unused:UNUSED_PAD src0_sel:DWORD
	v_pk_add_f32 v[92:93], v[92:93], v[106:107]
	v_pk_add_f32 v[90:91], v[90:91], v[104:105]
	v_cvt_f16_f32_e32 v106, v92
	v_cvt_f16_f32_e32 v104, v90
	v_cvt_f16_f32_sdwa v105, v91 dst_sel:WORD_1 dst_unused:UNUSED_PAD src0_sel:DWORD
	v_cvt_f16_f32_sdwa v107, v93 dst_sel:WORD_1 dst_unused:UNUSED_PAD src0_sel:DWORD
	v_or_b32_e32 v98, 32, v140
	s_waitcnt lgkmcnt(0)
	v_mov_b32_e32 v99, v141
	v_cvt_f16_f32_e32 v124, v118
	v_cvt_f16_f32_sdwa v125, v119 dst_sel:WORD_1 dst_unused:UNUSED_PAD src0_sel:DWORD
	v_or_b32_e32 v110, v123, v122
	v_lshlrev_b64 v[122:123], 11, v[98:99]
	v_lshl_add_u64 v[122:123], s[24:25], 0, v[122:123]
	v_mul_f32_e32 v91, v91, v91
	v_lshl_add_u64 v[122:123], v[138:139], 1, v[122:123]
	v_or_b32_e32 v104, v105, v104
	v_or_b32_e32 v105, v107, v106
	v_fmac_f32_e32 v91, v90, v90
	v_mul_f32_e32 v90, v93, v93
	v_pk_add_f32 v[88:89], v[88:89], v[114:115]
	v_pk_add_f32 v[86:87], v[86:87], v[108:109]
	v_or_b32_e32 v111, v125, v124
	v_mov_b32_e32 v242, v104
	v_mov_b32_e32 v243, v105
	v_fmac_f32_e32 v90, v92, v92
	v_cvt_f16_f32_e32 v92, v86
	v_cvt_f16_f32_sdwa v93, v87 dst_sel:WORD_1 dst_unused:UNUSED_PAD src0_sel:DWORD
	v_cvt_f16_f32_e32 v104, v88
	v_cvt_f16_f32_sdwa v105, v89 dst_sel:WORD_1 dst_unused:UNUSED_PAD src0_sel:DWORD
	v_mov_b32_e32 v240, v110
	v_mov_b32_e32 v241, v111
	v_mbcnt_lo_u32_b32 v222, -1, 0
	v_mbcnt_hi_u32_b32 v222, -1, v222
	v_bfe_u32 v222, v222, 4, 1
	v_mul_u32_u24_e32 v222, 24, v222
	v_mov_b32_e32 v223, 0
	v_permlane16_swap_b32_e32 v240, v242
	v_permlane16_swap_b32_e32 v241, v243
	v_lshl_add_u64 v[222:223], v[122:123], 0, v[222:223]
	global_store_dwordx4 v[222:223], v[240:243], off sc1
	v_mul_f32_e32 v110, v121, v121
	v_mul_f32_e32 v111, v119, v119
	v_fmac_f32_e32 v110, v120, v120
	v_fmac_f32_e32 v111, v118, v118
	v_add_f32_e32 v110, v110, v111
	v_add_f32_e32 v90, v91, v90
	v_mul_f32_e32 v87, v87, v87
	v_add_f32_e32 v106, v110, v90
	v_or_b32_e32 v90, v93, v92
	v_or_b32_e32 v91, v105, v104
	v_fmac_f32_e32 v87, v86, v86
	v_mul_f32_e32 v86, v89, v89
	v_pk_add_f32 v[84:85], v[84:85], v[116:117]
	v_pk_add_f32 v[82:83], v[82:83], v[112:113]
	v_mov_b32_e32 v244, v90
	v_mov_b32_e32 v245, v91
	v_fmac_f32_e32 v86, v88, v88
	v_cvt_f16_f32_e32 v88, v82
	v_cvt_f16_f32_sdwa v89, v83 dst_sel:WORD_1 dst_unused:UNUSED_PAD src0_sel:DWORD
	v_cvt_f16_f32_e32 v90, v84
	v_cvt_f16_f32_sdwa v91, v85 dst_sel:WORD_1 dst_unused:UNUSED_PAD src0_sel:DWORD
	v_mul_f32_e32 v83, v83, v83
	v_fmac_f32_e32 v83, v82, v82
	v_mul_f32_e32 v82, v85, v85
	v_add_f32_e32 v86, v87, v86
	v_fmac_f32_e32 v82, v84, v84
	v_add_f32_e32 v92, v106, v86
	v_or_b32_e32 v86, v89, v88
	v_or_b32_e32 v87, v91, v90
	v_add_f32_e32 v82, v83, v82
	v_mov_b32_e32 v246, v86
	v_mov_b32_e32 v247, v87
	v_mbcnt_lo_u32_b32 v222, -1, 0
	v_mbcnt_hi_u32_b32 v222, -1, v222
	v_bfe_u32 v222, v222, 4, 1
	v_mul_u32_u24_e32 v222, 24, v222
	v_mov_b32_e32 v223, 0
	v_permlane16_swap_b32_e32 v244, v246
	v_permlane16_swap_b32_e32 v245, v247
	v_lshl_add_u64 v[222:223], v[122:123], 0, v[222:223]
	global_store_dwordx4 v[222:223], v[244:247], off offset:256 sc1
	v_add_f32_e32 v82, v92, v82
	v_mov_b32_e32 v83, v82
	s_nop 1
	v_permlane16_swap_b32_e32 v83, v82
	s_waitcnt lgkmcnt(0)
	v_add_f32_e32 v82, v82, v83
	s_nop 0
	v_mov_b32_e32 v83, v82
	s_nop 1
	v_permlane32_swap_b32_e32 v83, v82
	s_and_saveexec_b64 s[22:23], s[0:1]
	s_cbranch_execz .LBB0_1996
	v_lshlrev_b64 v[84:85], 6, v[98:99]
	v_lshl_add_u64 v[84:85], s[20:21], 0, v[84:85]
	s_waitcnt lgkmcnt(0)
	v_add_f32_e32 v82, v82, v83
	global_store_dword v[84:85], v82, off
.LBB0_1996:
	s_or_b64 exec, exec, s[22:23]
	s_waitcnt vmcnt(5)
	v_cvt_f32_f16_sdwa v85, v102 dst_sel:DWORD dst_unused:UNUSED_PAD src0_sel:WORD_1
	v_cvt_f32_f16_e32 v84, v102
	v_cvt_f32_f16_sdwa v87, v103 dst_sel:DWORD dst_unused:UNUSED_PAD src0_sel:WORD_1
	v_cvt_f32_f16_e32 v86, v103
	s_mov_b32 s13, 0x40000
	s_waitcnt vmcnt(3)
	v_cvt_f32_f16_sdwa v93, v96 dst_sel:DWORD dst_unused:UNUSED_PAD src0_sel:WORD_1
	v_cvt_f32_f16_e32 v92, v96
	v_cvt_f32_f16_sdwa v99, v97 dst_sel:DWORD dst_unused:UNUSED_PAD src0_sel:WORD_1
	v_cvt_f32_f16_e32 v98, v97
	s_waitcnt vmcnt(2)
	v_cvt_f32_f16_sdwa v97, v94 dst_sel:DWORD dst_unused:UNUSED_PAD src0_sel:WORD_1
	v_cvt_f32_f16_e32 v96, v94
	v_add_co_u32_e32 v94, vcc, s13, v144
	v_cvt_f32_f16_sdwa v89, v100 dst_sel:DWORD dst_unused:UNUSED_PAD src0_sel:WORD_1
	v_cvt_f32_f16_e32 v88, v100
	v_cvt_f32_f16_sdwa v91, v101 dst_sel:DWORD dst_unused:UNUSED_PAD src0_sel:WORD_1
	v_cvt_f32_f16_e32 v90, v101
	v_cvt_f32_f16_sdwa v101, v95 dst_sel:DWORD dst_unused:UNUSED_PAD src0_sel:WORD_1
	v_cvt_f32_f16_e32 v100, v95
	v_addc_co_u32_e32 v95, vcc, 0, v145, vcc
	v_pk_add_f32 v[102:103], v[80:81], v[86:87]
	v_pk_add_f32 v[104:105], v[78:79], v[84:85]
	global_load_dwordx2 v[86:87], v[94:95], off
	global_load_dwordx2 v[84:85], v[94:95], off offset:32
	global_load_dwordx2 v[80:81], v[94:95], off offset:256
	global_load_dwordx2 v[78:79], v[94:95], off offset:288
	v_cvt_f16_f32_e32 v106, v104
	v_cvt_f16_f32_sdwa v107, v105 dst_sel:WORD_1 dst_unused:UNUSED_PAD src0_sel:DWORD
	v_pk_add_f32 v[76:77], v[76:77], v[90:91]
	v_pk_add_f32 v[74:75], v[74:75], v[88:89]
	v_cvt_f16_f32_e32 v90, v76
	v_cvt_f16_f32_e32 v88, v74
	v_cvt_f16_f32_sdwa v89, v75 dst_sel:WORD_1 dst_unused:UNUSED_PAD src0_sel:DWORD
	v_cvt_f16_f32_sdwa v91, v77 dst_sel:WORD_1 dst_unused:UNUSED_PAD src0_sel:DWORD
	v_or_b32_e32 v82, 48, v140
	s_waitcnt lgkmcnt(0)
	v_mov_b32_e32 v83, v141
	v_cvt_f16_f32_e32 v108, v102
	v_cvt_f16_f32_sdwa v109, v103 dst_sel:WORD_1 dst_unused:UNUSED_PAD src0_sel:DWORD
	v_or_b32_e32 v94, v107, v106
	v_lshlrev_b64 v[106:107], 11, v[82:83]
	v_lshl_add_u64 v[106:107], s[24:25], 0, v[106:107]
	v_mul_f32_e32 v75, v75, v75
	v_lshl_add_u64 v[106:107], v[138:139], 1, v[106:107]
	v_or_b32_e32 v88, v89, v88
	v_or_b32_e32 v89, v91, v90
	v_fmac_f32_e32 v75, v74, v74
	v_mul_f32_e32 v74, v77, v77
	v_pk_add_f32 v[72:73], v[72:73], v[98:99]
	v_pk_add_f32 v[70:71], v[70:71], v[92:93]
	v_or_b32_e32 v95, v109, v108
	v_mov_b32_e32 v242, v88
	v_mov_b32_e32 v243, v89
	v_fmac_f32_e32 v74, v76, v76
	v_cvt_f16_f32_e32 v76, v70
	v_cvt_f16_f32_sdwa v77, v71 dst_sel:WORD_1 dst_unused:UNUSED_PAD src0_sel:DWORD
	v_cvt_f16_f32_e32 v88, v72
	v_cvt_f16_f32_sdwa v89, v73 dst_sel:WORD_1 dst_unused:UNUSED_PAD src0_sel:DWORD
	v_mov_b32_e32 v240, v94
	v_mov_b32_e32 v241, v95
	v_mbcnt_lo_u32_b32 v222, -1, 0
	v_mbcnt_hi_u32_b32 v222, -1, v222
	v_bfe_u32 v222, v222, 4, 1
	v_mul_u32_u24_e32 v222, 24, v222
	v_mov_b32_e32 v223, 0
	v_permlane16_swap_b32_e32 v240, v242
	v_permlane16_swap_b32_e32 v241, v243
	v_lshl_add_u64 v[222:223], v[106:107], 0, v[222:223]
	global_store_dwordx4 v[222:223], v[240:243], off sc1
	v_mul_f32_e32 v94, v105, v105
	v_mul_f32_e32 v95, v103, v103
	v_fmac_f32_e32 v94, v104, v104
	v_fmac_f32_e32 v95, v102, v102
	v_add_f32_e32 v94, v94, v95
	v_add_f32_e32 v74, v75, v74
	v_mul_f32_e32 v71, v71, v71
	v_add_f32_e32 v90, v94, v74
	v_or_b32_e32 v74, v77, v76
	v_or_b32_e32 v75, v89, v88
	v_fmac_f32_e32 v71, v70, v70
	v_mul_f32_e32 v70, v73, v73
	v_pk_add_f32 v[68:69], v[68:69], v[100:101]
	v_pk_add_f32 v[66:67], v[66:67], v[96:97]
	v_mov_b32_e32 v244, v74
	v_mov_b32_e32 v245, v75
	v_fmac_f32_e32 v70, v72, v72
	v_cvt_f16_f32_e32 v72, v66
	v_cvt_f16_f32_sdwa v73, v67 dst_sel:WORD_1 dst_unused:UNUSED_PAD src0_sel:DWORD
	v_cvt_f16_f32_e32 v74, v68
	v_cvt_f16_f32_sdwa v75, v69 dst_sel:WORD_1 dst_unused:UNUSED_PAD src0_sel:DWORD
	v_mul_f32_e32 v67, v67, v67
	v_fmac_f32_e32 v67, v66, v66
	v_mul_f32_e32 v66, v69, v69
	v_add_f32_e32 v70, v71, v70
	v_fmac_f32_e32 v66, v68, v68
	v_add_f32_e32 v76, v90, v70
	v_or_b32_e32 v70, v73, v72
	v_or_b32_e32 v71, v75, v74
	v_add_f32_e32 v66, v67, v66
	v_mov_b32_e32 v246, v70
	v_mov_b32_e32 v247, v71
	v_mbcnt_lo_u32_b32 v222, -1, 0
	v_mbcnt_hi_u32_b32 v222, -1, v222
	v_bfe_u32 v222, v222, 4, 1
	v_mul_u32_u24_e32 v222, 24, v222
	v_mov_b32_e32 v223, 0
	v_permlane16_swap_b32_e32 v244, v246
	v_permlane16_swap_b32_e32 v245, v247
	v_lshl_add_u64 v[222:223], v[106:107], 0, v[222:223]
	global_store_dwordx4 v[222:223], v[244:247], off offset:256 sc1
	v_add_f32_e32 v66, v76, v66
	v_mov_b32_e32 v67, v66
	s_nop 1
	v_permlane16_swap_b32_e32 v67, v66
	s_waitcnt lgkmcnt(0)
	v_add_f32_e32 v66, v66, v67
	s_nop 0
	v_mov_b32_e32 v67, v66
	s_nop 1
	v_permlane32_swap_b32_e32 v67, v66
	s_and_saveexec_b64 s[22:23], s[0:1]
	s_cbranch_execz .LBB0_1998
	v_lshlrev_b64 v[68:69], 6, v[82:83]
	v_lshl_add_u64 v[68:69], s[20:21], 0, v[68:69]
	s_waitcnt lgkmcnt(0)
	v_add_f32_e32 v66, v66, v67
	global_store_dword v[68:69], v66, off
.LBB0_1998:
	s_or_b64 exec, exec, s[22:23]
	s_waitcnt vmcnt(5)
	v_cvt_f32_f16_sdwa v71, v86 dst_sel:DWORD dst_unused:UNUSED_PAD src0_sel:WORD_1
	v_cvt_f32_f16_e32 v70, v86
	v_cvt_f32_f16_sdwa v73, v87 dst_sel:DWORD dst_unused:UNUSED_PAD src0_sel:WORD_1
	v_cvt_f32_f16_e32 v72, v87
	v_lshl_add_u64 v[68:69], v[140:141], 0, s[96:97]
	s_waitcnt lgkmcnt(0)
	v_lshlrev_b64 v[66:67], 11, v[68:69]
	v_or_b32_e32 v88, 0x8000, v66
	v_mov_b32_e32 v89, v67
	v_lshl_add_u64 v[88:89], v[142:143], 0, v[88:89]
	v_pk_add_f32 v[90:91], v[64:65], v[72:73]
	v_pk_add_f32 v[92:93], v[62:63], v[70:71]
	global_load_dwordx2 v[72:73], v[88:89], off
	global_load_dwordx2 v[70:71], v[88:89], off offset:32
	global_load_dwordx2 v[64:65], v[88:89], off offset:256
	global_load_dwordx2 v[62:63], v[88:89], off offset:288
	s_waitcnt vmcnt(8)
	v_cvt_f32_f16_sdwa v75, v84 dst_sel:DWORD dst_unused:UNUSED_PAD src0_sel:WORD_1
	v_cvt_f32_f16_e32 v74, v84
	v_cvt_f32_f16_sdwa v77, v85 dst_sel:DWORD dst_unused:UNUSED_PAD src0_sel:WORD_1
	v_cvt_f32_f16_e32 v76, v85
	s_waitcnt vmcnt(7)
	v_cvt_f32_f16_sdwa v83, v80 dst_sel:DWORD dst_unused:UNUSED_PAD src0_sel:WORD_1
	v_pk_add_f32 v[58:59], v[58:59], v[74:75]
	v_cvt_f32_f16_e32 v82, v80
	v_pk_add_f32 v[60:61], v[60:61], v[76:77]
	v_cvt_f32_f16_sdwa v85, v81 dst_sel:DWORD dst_unused:UNUSED_PAD src0_sel:WORD_1
	v_cvt_f32_f16_e32 v84, v81
	v_cvt_f16_f32_e32 v74, v58
	v_cvt_f16_f32_sdwa v75, v59 dst_sel:WORD_1 dst_unused:UNUSED_PAD src0_sel:DWORD
	v_cvt_f16_f32_e32 v76, v60
	v_cvt_f16_f32_sdwa v77, v61 dst_sel:WORD_1 dst_unused:UNUSED_PAD src0_sel:DWORD
	s_waitcnt vmcnt(6)
	v_cvt_f32_f16_sdwa v81, v78 dst_sel:DWORD dst_unused:UNUSED_PAD src0_sel:WORD_1
	v_cvt_f32_f16_e32 v80, v78
	v_cvt_f16_f32_e32 v78, v92
	v_cvt_f16_f32_sdwa v94, v93 dst_sel:WORD_1 dst_unused:UNUSED_PAD src0_sel:DWORD
	v_cvt_f16_f32_e32 v95, v90
	v_cvt_f16_f32_sdwa v96, v91 dst_sel:WORD_1 dst_unused:UNUSED_PAD src0_sel:DWORD
	v_lshl_add_u64 v[88:89], s[24:25], 0, v[66:67]
	v_mul_f32_e32 v59, v59, v59
	v_lshl_add_u64 v[88:89], v[138:139], 1, v[88:89]
	v_or_b32_e32 v74, v75, v74
	v_or_b32_e32 v75, v77, v76
	v_fmac_f32_e32 v59, v58, v58
	v_mul_f32_e32 v58, v61, v61
	v_pk_add_f32 v[56:57], v[56:57], v[84:85]
	v_pk_add_f32 v[54:55], v[54:55], v[82:83]
	v_cvt_f32_f16_sdwa v87, v79 dst_sel:DWORD dst_unused:UNUSED_PAD src0_sel:WORD_1
	v_cvt_f32_f16_e32 v86, v79
	v_or_b32_e32 v78, v94, v78
	v_or_b32_e32 v79, v96, v95
	v_mov_b32_e32 v242, v74
	v_mov_b32_e32 v243, v75
	v_fmac_f32_e32 v58, v60, v60
	v_cvt_f16_f32_e32 v60, v54
	v_cvt_f16_f32_sdwa v61, v55 dst_sel:WORD_1 dst_unused:UNUSED_PAD src0_sel:DWORD
	v_cvt_f16_f32_e32 v74, v56
	v_cvt_f16_f32_sdwa v75, v57 dst_sel:WORD_1 dst_unused:UNUSED_PAD src0_sel:DWORD
	v_mov_b32_e32 v240, v78
	v_mov_b32_e32 v241, v79
	v_mbcnt_lo_u32_b32 v222, -1, 0
	v_mbcnt_hi_u32_b32 v222, -1, v222
	v_bfe_u32 v222, v222, 4, 1
	v_mul_u32_u24_e32 v222, 24, v222
	v_mov_b32_e32 v223, 0
	v_permlane16_swap_b32_e32 v240, v242
	v_permlane16_swap_b32_e32 v241, v243
	v_lshl_add_u64 v[222:223], v[88:89], 0, v[222:223]
	global_store_dwordx4 v[222:223], v[240:243], off sc1
	v_mul_f32_e32 v78, v93, v93
	v_mul_f32_e32 v79, v91, v91
	v_fmac_f32_e32 v78, v92, v92
	v_fmac_f32_e32 v79, v90, v90
	v_add_f32_e32 v78, v78, v79
	v_add_f32_e32 v58, v59, v58
	v_mul_f32_e32 v55, v55, v55
	v_add_f32_e32 v76, v78, v58
	v_or_b32_e32 v58, v61, v60
	v_or_b32_e32 v59, v75, v74
	v_fmac_f32_e32 v55, v54, v54
	v_mul_f32_e32 v54, v57, v57
	v_pk_add_f32 v[52:53], v[52:53], v[86:87]
	v_pk_add_f32 v[50:51], v[50:51], v[80:81]
	v_mov_b32_e32 v244, v58
	v_mov_b32_e32 v245, v59
	v_fmac_f32_e32 v54, v56, v56
	v_cvt_f16_f32_e32 v56, v50
	v_cvt_f16_f32_sdwa v57, v51 dst_sel:WORD_1 dst_unused:UNUSED_PAD src0_sel:DWORD
	v_cvt_f16_f32_e32 v58, v52
	v_cvt_f16_f32_sdwa v59, v53 dst_sel:WORD_1 dst_unused:UNUSED_PAD src0_sel:DWORD
	v_mul_f32_e32 v51, v51, v51
	v_fmac_f32_e32 v51, v50, v50
	v_mul_f32_e32 v50, v53, v53
	v_add_f32_e32 v54, v55, v54
	v_fmac_f32_e32 v50, v52, v52
	v_add_f32_e32 v60, v76, v54
	v_or_b32_e32 v54, v57, v56
	v_or_b32_e32 v55, v59, v58
	v_add_f32_e32 v50, v51, v50
	v_mov_b32_e32 v246, v54
	v_mov_b32_e32 v247, v55
	v_mbcnt_lo_u32_b32 v222, -1, 0
	v_mbcnt_hi_u32_b32 v222, -1, v222
	v_bfe_u32 v222, v222, 4, 1
	v_mul_u32_u24_e32 v222, 24, v222
	v_mov_b32_e32 v223, 0
	v_permlane16_swap_b32_e32 v244, v246
	v_permlane16_swap_b32_e32 v245, v247
	v_lshl_add_u64 v[222:223], v[88:89], 0, v[222:223]
	global_store_dwordx4 v[222:223], v[244:247], off offset:256 sc1
	v_add_f32_e32 v50, v60, v50
	v_mov_b32_e32 v51, v50
	s_nop 1
	v_permlane16_swap_b32_e32 v51, v50
	s_waitcnt lgkmcnt(0)
	v_add_f32_e32 v50, v50, v51
	s_nop 0
	v_mov_b32_e32 v51, v50
	s_nop 1
	v_permlane32_swap_b32_e32 v51, v50
	s_and_saveexec_b64 s[22:23], s[0:1]
	s_cbranch_execz .LBB0_2000
	v_lshlrev_b64 v[52:53], 6, v[68:69]
	v_lshl_add_u64 v[52:53], s[20:21], 0, v[52:53]
	s_waitcnt lgkmcnt(0)
	v_add_f32_e32 v50, v50, v51
	global_store_dword v[52:53], v50, off
.LBB0_2000:
	s_or_b64 exec, exec, s[22:23]
	s_waitcnt vmcnt(5)
	v_cvt_f32_f16_sdwa v53, v72 dst_sel:DWORD dst_unused:UNUSED_PAD src0_sel:WORD_1
	v_cvt_f32_f16_e32 v52, v72
	v_cvt_f32_f16_sdwa v55, v73 dst_sel:DWORD dst_unused:UNUSED_PAD src0_sel:WORD_1
	v_cvt_f32_f16_e32 v54, v73
	s_waitcnt vmcnt(4)
	v_cvt_f32_f16_sdwa v57, v70 dst_sel:DWORD dst_unused:UNUSED_PAD src0_sel:WORD_1
	v_cvt_f32_f16_e32 v56, v70
	v_cvt_f32_f16_sdwa v59, v71 dst_sel:DWORD dst_unused:UNUSED_PAD src0_sel:WORD_1
	v_cvt_f32_f16_e32 v58, v71
	s_waitcnt vmcnt(3)
	v_cvt_f32_f16_sdwa v61, v64 dst_sel:DWORD dst_unused:UNUSED_PAD src0_sel:WORD_1
	v_cvt_f32_f16_e32 v60, v64
	v_cvt_f32_f16_sdwa v69, v65 dst_sel:DWORD dst_unused:UNUSED_PAD src0_sel:WORD_1
	v_cvt_f32_f16_e32 v68, v65
	s_waitcnt vmcnt(2)
	v_cvt_f32_f16_sdwa v65, v62 dst_sel:DWORD dst_unused:UNUSED_PAD src0_sel:WORD_1
	v_cvt_f32_f16_e32 v64, v62
	v_cvt_f32_f16_sdwa v71, v63 dst_sel:DWORD dst_unused:UNUSED_PAD src0_sel:WORD_1
	v_cvt_f32_f16_e32 v70, v63
	v_or_b32_e32 v62, 0x10000, v66
	v_mov_b32_e32 v63, v67
	v_lshl_add_u64 v[62:63], v[142:143], 0, v[62:63]
	v_pk_add_f32 v[72:73], v[48:49], v[54:55]
	v_pk_add_f32 v[74:75], v[46:47], v[52:53]
	global_load_dwordx2 v[54:55], v[62:63], off
	global_load_dwordx2 v[52:53], v[62:63], off offset:32
	global_load_dwordx2 v[48:49], v[62:63], off offset:256
	global_load_dwordx2 v[46:47], v[62:63], off offset:288
	v_cvt_f16_f32_e32 v76, v74
	v_cvt_f16_f32_sdwa v77, v75 dst_sel:WORD_1 dst_unused:UNUSED_PAD src0_sel:DWORD
	v_pk_add_f32 v[44:45], v[44:45], v[58:59]
	v_pk_add_f32 v[42:43], v[42:43], v[56:57]
	s_mov_b64 s[22:23], 0x90
	v_cvt_f16_f32_e32 v56, v42
	v_cvt_f16_f32_sdwa v57, v43 dst_sel:WORD_1 dst_unused:UNUSED_PAD src0_sel:DWORD
	v_cvt_f16_f32_e32 v58, v44
	v_cvt_f16_f32_sdwa v59, v45 dst_sel:WORD_1 dst_unused:UNUSED_PAD src0_sel:DWORD
	s_waitcnt lgkmcnt(0)
	v_lshl_add_u64 v[50:51], v[140:141], 0, s[22:23]
	v_cvt_f16_f32_e32 v78, v72
	v_cvt_f16_f32_sdwa v79, v73 dst_sel:WORD_1 dst_unused:UNUSED_PAD src0_sel:DWORD
	v_or_b32_e32 v62, v77, v76
	v_lshlrev_b64 v[76:77], 11, v[50:51]
	v_lshl_add_u64 v[76:77], s[24:25], 0, v[76:77]
	v_mul_f32_e32 v43, v43, v43
	v_lshl_add_u64 v[76:77], v[138:139], 1, v[76:77]
	v_or_b32_e32 v56, v57, v56
	v_or_b32_e32 v57, v59, v58
	v_fmac_f32_e32 v43, v42, v42
	v_mul_f32_e32 v42, v45, v45
	v_pk_add_f32 v[40:41], v[40:41], v[68:69]
	v_pk_add_f32 v[38:39], v[38:39], v[60:61]
	v_or_b32_e32 v63, v79, v78
	v_mov_b32_e32 v242, v56
	v_mov_b32_e32 v243, v57
	v_fmac_f32_e32 v42, v44, v44
	v_cvt_f16_f32_e32 v44, v38
	v_cvt_f16_f32_sdwa v45, v39 dst_sel:WORD_1 dst_unused:UNUSED_PAD src0_sel:DWORD
	v_cvt_f16_f32_e32 v56, v40
	v_cvt_f16_f32_sdwa v57, v41 dst_sel:WORD_1 dst_unused:UNUSED_PAD src0_sel:DWORD
	v_mov_b32_e32 v240, v62
	v_mov_b32_e32 v241, v63
	v_mbcnt_lo_u32_b32 v222, -1, 0
	v_mbcnt_hi_u32_b32 v222, -1, v222
	v_bfe_u32 v222, v222, 4, 1
	v_mul_u32_u24_e32 v222, 24, v222
	v_mov_b32_e32 v223, 0
	v_permlane16_swap_b32_e32 v240, v242
	v_permlane16_swap_b32_e32 v241, v243
	v_lshl_add_u64 v[222:223], v[76:77], 0, v[222:223]
	global_store_dwordx4 v[222:223], v[240:243], off sc1
	v_mul_f32_e32 v62, v75, v75
	v_mul_f32_e32 v63, v73, v73
	v_fmac_f32_e32 v62, v74, v74
	v_fmac_f32_e32 v63, v72, v72
	v_add_f32_e32 v62, v62, v63
	v_add_f32_e32 v42, v43, v42
	v_mul_f32_e32 v39, v39, v39
	v_add_f32_e32 v58, v62, v42
	v_or_b32_e32 v42, v45, v44
	v_or_b32_e32 v43, v57, v56
	v_fmac_f32_e32 v39, v38, v38
	v_mul_f32_e32 v38, v41, v41
	v_pk_add_f32 v[36:37], v[36:37], v[70:71]
	v_pk_add_f32 v[34:35], v[34:35], v[64:65]
	v_mov_b32_e32 v244, v42
	v_mov_b32_e32 v245, v43
	v_fmac_f32_e32 v38, v40, v40
	v_cvt_f16_f32_e32 v40, v34
	v_cvt_f16_f32_sdwa v41, v35 dst_sel:WORD_1 dst_unused:UNUSED_PAD src0_sel:DWORD
	v_cvt_f16_f32_e32 v42, v36
	v_cvt_f16_f32_sdwa v43, v37 dst_sel:WORD_1 dst_unused:UNUSED_PAD src0_sel:DWORD
	v_mul_f32_e32 v35, v35, v35
	v_fmac_f32_e32 v35, v34, v34
	v_mul_f32_e32 v34, v37, v37
	v_add_f32_e32 v38, v39, v38
	v_fmac_f32_e32 v34, v36, v36
	v_add_f32_e32 v44, v58, v38
	v_or_b32_e32 v38, v41, v40
	v_or_b32_e32 v39, v43, v42
	v_add_f32_e32 v34, v35, v34
	v_mov_b32_e32 v246, v38
	v_mov_b32_e32 v247, v39
	v_mbcnt_lo_u32_b32 v222, -1, 0
	v_mbcnt_hi_u32_b32 v222, -1, v222
	v_bfe_u32 v222, v222, 4, 1
	v_mul_u32_u24_e32 v222, 24, v222
	v_mov_b32_e32 v223, 0
	v_permlane16_swap_b32_e32 v244, v246
	v_permlane16_swap_b32_e32 v245, v247
	v_lshl_add_u64 v[222:223], v[76:77], 0, v[222:223]
	global_store_dwordx4 v[222:223], v[244:247], off offset:256 sc1
	v_add_f32_e32 v34, v44, v34
	v_mov_b32_e32 v35, v34
	s_nop 1
	v_permlane16_swap_b32_e32 v35, v34
	s_waitcnt lgkmcnt(0)
	v_add_f32_e32 v34, v34, v35
	s_nop 0
	v_mov_b32_e32 v35, v34
	s_nop 1
	v_permlane32_swap_b32_e32 v35, v34
	s_and_saveexec_b64 s[22:23], s[0:1]
	s_cbranch_execz .LBB0_2002
	v_lshlrev_b64 v[36:37], 6, v[50:51]
	v_lshl_add_u64 v[36:37], s[20:21], 0, v[36:37]
	s_waitcnt lgkmcnt(0)
	v_add_f32_e32 v34, v34, v35
	global_store_dword v[36:37], v34, off
.LBB0_2002:
	s_or_b64 exec, exec, s[22:23]
	s_waitcnt vmcnt(5)
	v_cvt_f32_f16_sdwa v37, v54 dst_sel:DWORD dst_unused:UNUSED_PAD src0_sel:WORD_1
	v_cvt_f32_f16_e32 v36, v54
	v_cvt_f32_f16_sdwa v39, v55 dst_sel:DWORD dst_unused:UNUSED_PAD src0_sel:WORD_1
	v_cvt_f32_f16_e32 v38, v55
	v_or_b32_e32 v66, 0x18000, v66
	s_waitcnt vmcnt(4)
	v_cvt_f32_f16_sdwa v41, v52 dst_sel:DWORD dst_unused:UNUSED_PAD src0_sel:WORD_1
	v_cvt_f32_f16_e32 v40, v52
	v_cvt_f32_f16_sdwa v43, v53 dst_sel:DWORD dst_unused:UNUSED_PAD src0_sel:WORD_1
	v_cvt_f32_f16_e32 v42, v53
	s_waitcnt vmcnt(3)
	v_cvt_f32_f16_sdwa v45, v48 dst_sel:DWORD dst_unused:UNUSED_PAD src0_sel:WORD_1
	v_cvt_f32_f16_e32 v44, v48
	v_cvt_f32_f16_sdwa v51, v49 dst_sel:DWORD dst_unused:UNUSED_PAD src0_sel:WORD_1
	v_cvt_f32_f16_e32 v50, v49
	s_waitcnt vmcnt(2)
	v_cvt_f32_f16_sdwa v49, v46 dst_sel:DWORD dst_unused:UNUSED_PAD src0_sel:WORD_1
	v_cvt_f32_f16_e32 v48, v46
	v_cvt_f32_f16_sdwa v53, v47 dst_sel:DWORD dst_unused:UNUSED_PAD src0_sel:WORD_1
	v_cvt_f32_f16_e32 v52, v47
	v_lshl_add_u64 v[46:47], v[142:143], 0, v[66:67]
	v_pk_add_f32 v[54:55], v[32:33], v[38:39]
	v_pk_add_f32 v[56:57], v[30:31], v[36:37]
	global_load_dwordx2 v[38:39], v[46:47], off
	global_load_dwordx2 v[36:37], v[46:47], off offset:32
	global_load_dwordx2 v[32:33], v[46:47], off offset:256
	global_load_dwordx2 v[30:31], v[46:47], off offset:288
	v_cvt_f16_f32_e32 v58, v56
	v_cvt_f16_f32_sdwa v59, v57 dst_sel:WORD_1 dst_unused:UNUSED_PAD src0_sel:DWORD
	v_pk_add_f32 v[28:29], v[28:29], v[42:43]
	v_pk_add_f32 v[26:27], v[26:27], v[40:41]
	s_mov_b64 s[22:23], 0xa0
	v_cvt_f16_f32_e32 v40, v26
	v_cvt_f16_f32_sdwa v41, v27 dst_sel:WORD_1 dst_unused:UNUSED_PAD src0_sel:DWORD
	v_cvt_f16_f32_e32 v42, v28
	v_cvt_f16_f32_sdwa v43, v29 dst_sel:WORD_1 dst_unused:UNUSED_PAD src0_sel:DWORD
	s_waitcnt lgkmcnt(0)
	v_lshl_add_u64 v[34:35], v[140:141], 0, s[22:23]
	v_cvt_f16_f32_e32 v60, v54
	v_cvt_f16_f32_sdwa v61, v55 dst_sel:WORD_1 dst_unused:UNUSED_PAD src0_sel:DWORD
	v_or_b32_e32 v46, v59, v58
	v_lshlrev_b64 v[58:59], 11, v[34:35]
	v_lshl_add_u64 v[58:59], s[24:25], 0, v[58:59]
	v_mul_f32_e32 v27, v27, v27
	v_lshl_add_u64 v[58:59], v[138:139], 1, v[58:59]
	v_or_b32_e32 v40, v41, v40
	v_or_b32_e32 v41, v43, v42
	v_fmac_f32_e32 v27, v26, v26
	v_mul_f32_e32 v26, v29, v29
	v_pk_add_f32 v[24:25], v[24:25], v[50:51]
	v_pk_add_f32 v[22:23], v[22:23], v[44:45]
	v_or_b32_e32 v47, v61, v60
	v_mov_b32_e32 v242, v40
	v_mov_b32_e32 v243, v41
	v_fmac_f32_e32 v26, v28, v28
	v_cvt_f16_f32_e32 v28, v22
	v_cvt_f16_f32_sdwa v29, v23 dst_sel:WORD_1 dst_unused:UNUSED_PAD src0_sel:DWORD
	v_cvt_f16_f32_e32 v40, v24
	v_cvt_f16_f32_sdwa v41, v25 dst_sel:WORD_1 dst_unused:UNUSED_PAD src0_sel:DWORD
	v_mov_b32_e32 v240, v46
	v_mov_b32_e32 v241, v47
	v_mbcnt_lo_u32_b32 v222, -1, 0
	v_mbcnt_hi_u32_b32 v222, -1, v222
	v_bfe_u32 v222, v222, 4, 1
	v_mul_u32_u24_e32 v222, 24, v222
	v_mov_b32_e32 v223, 0
	v_permlane16_swap_b32_e32 v240, v242
	v_permlane16_swap_b32_e32 v241, v243
	v_lshl_add_u64 v[222:223], v[58:59], 0, v[222:223]
	global_store_dwordx4 v[222:223], v[240:243], off sc1
	v_mul_f32_e32 v46, v57, v57
	v_mul_f32_e32 v47, v55, v55
	v_fmac_f32_e32 v46, v56, v56
	v_fmac_f32_e32 v47, v54, v54
	v_add_f32_e32 v46, v46, v47
	v_add_f32_e32 v26, v27, v26
	v_mul_f32_e32 v23, v23, v23
	v_add_f32_e32 v42, v46, v26
	v_or_b32_e32 v26, v29, v28
	v_or_b32_e32 v27, v41, v40
	v_fmac_f32_e32 v23, v22, v22
	v_mul_f32_e32 v22, v25, v25
	v_pk_add_f32 v[20:21], v[20:21], v[52:53]
	v_pk_add_f32 v[18:19], v[18:19], v[48:49]
	v_mov_b32_e32 v244, v26
	v_mov_b32_e32 v245, v27
	v_fmac_f32_e32 v22, v24, v24
	v_cvt_f16_f32_e32 v24, v18
	v_cvt_f16_f32_sdwa v25, v19 dst_sel:WORD_1 dst_unused:UNUSED_PAD src0_sel:DWORD
	v_cvt_f16_f32_e32 v26, v20
	v_cvt_f16_f32_sdwa v27, v21 dst_sel:WORD_1 dst_unused:UNUSED_PAD src0_sel:DWORD
	v_mul_f32_e32 v19, v19, v19
	v_fmac_f32_e32 v19, v18, v18
	v_mul_f32_e32 v18, v21, v21
	v_add_f32_e32 v22, v23, v22
	v_fmac_f32_e32 v18, v20, v20
	v_add_f32_e32 v28, v42, v22
	v_or_b32_e32 v22, v25, v24
	v_or_b32_e32 v23, v27, v26
	v_add_f32_e32 v18, v19, v18
	v_mov_b32_e32 v246, v22
	v_mov_b32_e32 v247, v23
	v_mbcnt_lo_u32_b32 v222, -1, 0
	v_mbcnt_hi_u32_b32 v222, -1, v222
	v_bfe_u32 v222, v222, 4, 1
	v_mul_u32_u24_e32 v222, 24, v222
	v_mov_b32_e32 v223, 0
	v_permlane16_swap_b32_e32 v244, v246
	v_permlane16_swap_b32_e32 v245, v247
	v_lshl_add_u64 v[222:223], v[58:59], 0, v[222:223]
	global_store_dwordx4 v[222:223], v[244:247], off offset:256 sc1
	v_add_f32_e32 v18, v28, v18
	v_mov_b32_e32 v19, v18
	s_nop 1
	v_permlane16_swap_b32_e32 v19, v18
	s_waitcnt lgkmcnt(0)
	v_add_f32_e32 v18, v18, v19
	s_nop 0
	v_mov_b32_e32 v19, v18
	s_nop 1
	v_permlane32_swap_b32_e32 v19, v18
	s_and_saveexec_b64 s[22:23], s[0:1]
	s_cbranch_execz .LBB0_2004
	v_lshlrev_b64 v[20:21], 6, v[34:35]
	v_lshl_add_u64 v[20:21], s[20:21], 0, v[20:21]
	s_waitcnt lgkmcnt(0)
	v_add_f32_e32 v18, v18, v19
	global_store_dword v[20:21], v18, off
.LBB0_2004:
	s_or_b64 exec, exec, s[22:23]
	s_waitcnt vmcnt(5)
	v_cvt_f32_f16_sdwa v21, v38 dst_sel:DWORD dst_unused:UNUSED_PAD src0_sel:WORD_1
	v_cvt_f32_f16_e32 v20, v38
	v_cvt_f32_f16_sdwa v23, v39 dst_sel:DWORD dst_unused:UNUSED_PAD src0_sel:WORD_1
	v_cvt_f32_f16_e32 v22, v39
	s_waitcnt vmcnt(4)
	v_cvt_f32_f16_sdwa v25, v36 dst_sel:DWORD dst_unused:UNUSED_PAD src0_sel:WORD_1
	v_cvt_f32_f16_e32 v24, v36
	v_pk_add_f32 v[14:15], v[14:15], v[20:21]
	v_cvt_f32_f16_sdwa v27, v37 dst_sel:DWORD dst_unused:UNUSED_PAD src0_sel:WORD_1
	v_cvt_f32_f16_e32 v26, v37
	v_cvt_f16_f32_e32 v20, v14
	v_cvt_f16_f32_sdwa v21, v15 dst_sel:WORD_1 dst_unused:UNUSED_PAD src0_sel:DWORD
	v_pk_add_f32 v[16:17], v[16:17], v[22:23]
	v_mul_f32_e32 v15, v15, v15
	v_fmac_f32_e32 v15, v14, v14
	v_mul_f32_e32 v14, v17, v17
	s_waitcnt vmcnt(3)
	v_cvt_f32_f16_sdwa v29, v32 dst_sel:DWORD dst_unused:UNUSED_PAD src0_sel:WORD_1
	v_cvt_f32_f16_e32 v28, v32
	v_fmac_f32_e32 v14, v16, v16
	v_pk_add_f32 v[10:11], v[10:11], v[24:25]
	v_cvt_f32_f16_sdwa v35, v33 dst_sel:DWORD dst_unused:UNUSED_PAD src0_sel:WORD_1
	v_cvt_f32_f16_e32 v34, v33
	v_or_b32_e32 v20, v21, v20
	v_cvt_f16_f32_e32 v21, v16
	v_add_f32_e32 v16, v15, v14
	v_pk_add_f32 v[12:13], v[12:13], v[26:27]
	v_cvt_f16_f32_e32 v14, v10
	v_cvt_f16_f32_sdwa v15, v11 dst_sel:WORD_1 dst_unused:UNUSED_PAD src0_sel:DWORD
	v_mul_f32_e32 v11, v11, v11
	v_fmac_f32_e32 v11, v10, v10
	v_mul_f32_e32 v10, v13, v13
	v_fmac_f32_e32 v10, v12, v12
	s_waitcnt vmcnt(2)
	v_cvt_f32_f16_sdwa v33, v30 dst_sel:DWORD dst_unused:UNUSED_PAD src0_sel:WORD_1
	v_cvt_f32_f16_e32 v32, v30
	v_add_f32_e32 v10, v11, v10
	v_pk_add_f32 v[6:7], v[6:7], v[28:29]
	v_or_b32_e32 v14, v15, v14
	v_cvt_f16_f32_e32 v15, v12
	v_add_f32_e32 v12, v16, v10
	v_pk_add_f32 v[8:9], v[8:9], v[34:35]
	v_cvt_f16_f32_e32 v10, v6
	v_cvt_f16_f32_sdwa v11, v7 dst_sel:WORD_1 dst_unused:UNUSED_PAD src0_sel:DWORD
	v_mul_f32_e32 v7, v7, v7
	v_fmac_f32_e32 v7, v6, v6
	v_mul_f32_e32 v6, v9, v9
	v_fmac_f32_e32 v6, v8, v8
	v_cvt_f32_f16_sdwa v37, v31 dst_sel:DWORD dst_unused:UNUSED_PAD src0_sel:WORD_1
	v_cvt_f32_f16_e32 v36, v31
	v_add_f32_e32 v6, v7, v6
	v_pk_add_f32 v[2:3], v[2:3], v[32:33]
	v_or_b32_e32 v10, v11, v10
	v_cvt_f16_f32_e32 v11, v8
	v_add_f32_e32 v8, v12, v6
	v_cvt_f16_f32_e32 v6, v2
	v_cvt_f16_f32_sdwa v7, v3 dst_sel:WORD_1 dst_unused:UNUSED_PAD src0_sel:DWORD
	v_cvt_f16_f32_sdwa v22, v17 dst_sel:WORD_1 dst_unused:UNUSED_PAD src0_sel:DWORD
	v_pk_add_f32 v[4:5], v[4:5], v[36:37]
	s_mov_b64 s[22:23], 0xb0
	v_cvt_f16_f32_sdwa v17, v13 dst_sel:WORD_1 dst_unused:UNUSED_PAD src0_sel:DWORD
	v_cvt_f16_f32_sdwa v13, v9 dst_sel:WORD_1 dst_unused:UNUSED_PAD src0_sel:DWORD
	v_or_b32_e32 v6, v7, v6
	v_cvt_f16_f32_e32 v7, v4
	v_cvt_f16_f32_sdwa v9, v5 dst_sel:WORD_1 dst_unused:UNUSED_PAD src0_sel:DWORD
	s_waitcnt lgkmcnt(0)
	v_lshl_add_u64 v[18:19], v[140:141], 0, s[22:23]
	v_mul_f32_e32 v3, v3, v3
	v_or_b32_e32 v21, v22, v21
	v_lshlrev_b64 v[22:23], 11, v[18:19]
	v_fmac_f32_e32 v3, v2, v2
	v_mul_f32_e32 v2, v5, v5
	v_lshl_add_u64 v[22:23], s[24:25], 0, v[22:23]
	v_fmac_f32_e32 v2, v4, v4
	v_lshl_add_u64 v[22:23], v[138:139], 1, v[22:23]
	v_or_b32_e32 v15, v17, v15
	v_or_b32_e32 v11, v13, v11
	v_or_b32_e32 v7, v9, v7
	v_add_f32_e32 v2, v3, v2
	v_mov_b32_e32 v240, v20
	v_mov_b32_e32 v241, v21
	v_mov_b32_e32 v242, v14
	v_mov_b32_e32 v243, v15
	v_mbcnt_lo_u32_b32 v222, -1, 0
	v_mbcnt_hi_u32_b32 v222, -1, v222
	v_bfe_u32 v222, v222, 4, 1
	v_mul_u32_u24_e32 v222, 24, v222
	v_mov_b32_e32 v223, 0
	v_permlane16_swap_b32_e32 v240, v242
	v_permlane16_swap_b32_e32 v241, v243
	v_lshl_add_u64 v[222:223], v[22:23], 0, v[222:223]
	global_store_dwordx4 v[222:223], v[240:243], off sc1
	v_mov_b32_e32 v244, v10
	v_mov_b32_e32 v245, v11
	v_mov_b32_e32 v246, v6
	v_mov_b32_e32 v247, v7
	v_mbcnt_lo_u32_b32 v222, -1, 0
	v_mbcnt_hi_u32_b32 v222, -1, v222
	v_bfe_u32 v222, v222, 4, 1
	v_mul_u32_u24_e32 v222, 24, v222
	v_mov_b32_e32 v223, 0
	v_permlane16_swap_b32_e32 v244, v246
	v_permlane16_swap_b32_e32 v245, v247
	v_lshl_add_u64 v[222:223], v[22:23], 0, v[222:223]
	global_store_dwordx4 v[222:223], v[244:247], off offset:256 sc1
	v_add_f32_e32 v2, v8, v2
	v_mov_b32_e32 v3, v2
	s_nop 1
	v_permlane16_swap_b32_e32 v3, v2
	s_waitcnt lgkmcnt(0)
	v_add_f32_e32 v2, v2, v3
	s_nop 0
	v_mov_b32_e32 v3, v2
	s_nop 1
	v_permlane32_swap_b32_e32 v3, v2
	s_and_saveexec_b64 s[22:23], s[0:1]
	s_cbranch_execz .LBB0_2006
	v_lshlrev_b64 v[4:5], 6, v[18:19]
	v_lshl_add_u64 v[4:5], s[20:21], 0, v[4:5]
	s_waitcnt lgkmcnt(0)
	v_add_f32_e32 v2, v2, v3
	global_store_dword v[4:5], v2, off

.LBB0_2492:
	s_lshl_b32 s22, s47, 2
	s_ashr_i32 s23, s22, 31
	s_lshl_b64 s[22:23], s[22:23], 2
	s_add_u32 s22, s24, s22
	s_addc_u32 s23, s25, s23
	s_add_u32 s22, s22, s44
	s_addc_u32 s23, s23, 0
	s_add_u32 s22, s22, 0x10380000
	s_addc_u32 s23, s23, 0
	s_and_b64 vcc, exec, s[6:7]
	s_cbranch_vccnz .LBB0_2496
	v_mov_b32_e32 v114, v1
	v_mbcnt_lo_u32_b32 v114, -1, v114
	v_mbcnt_hi_u32_b32 v114, -1, v114
	v_lshlrev_b32_e32 v114, 2, v114
	v_xor_b32_e32 v114, 64, v114
	ds_bpermute_b32 v114, v114, v118
	s_waitcnt lgkmcnt(0)
	v_add_f32_e32 v114, v118, v114
	v_mov_b32_e32 v115, v114
	s_nop 1
	v_permlane32_swap_b32_e32 v115, v114
	s_and_saveexec_b64 s[24:25], s[2:3]
	s_cbranch_execz .LBB0_2495
	v_lshlrev_b64 v[116:117], 6, v[140:141]
	v_lshl_add_u64 v[116:117], s[22:23], 0, v[116:117]
	s_waitcnt lgkmcnt(0)
	v_add_f32_e32 v114, v114, v115
	global_store_dword v[116:117], v114, off

.LBB0_2513:
	v_mov_b32_e32 v98, v1
	v_mbcnt_lo_u32_b32 v98, -1, v98
	v_mbcnt_hi_u32_b32 v98, -1, v98
	v_lshlrev_b32_e32 v98, 2, v98
	v_xor_b32_e32 v98, 64, v98
	ds_bpermute_b32 v98, v98, v102
	s_waitcnt lgkmcnt(0)
	v_add_f32_e32 v98, v102, v98
	v_mov_b32_e32 v99, v98
	s_nop 1
	v_permlane32_swap_b32_e32 v99, v98
	s_and_saveexec_b64 s[24:25], s[2:3]
	s_cbranch_execz .LBB0_2515
	v_lshlrev_b64 v[100:101], 6, v[122:123]
	v_lshl_add_u64 v[100:101], s[22:23], 0, v[100:101]
	s_waitcnt lgkmcnt(0)
	v_add_f32_e32 v98, v98, v99
	global_store_dword v[100:101], v98, off

.LBB0_2533:
	v_mov_b32_e32 v82, v1
	v_mbcnt_lo_u32_b32 v82, -1, v82
	v_mbcnt_hi_u32_b32 v82, -1, v82
	v_lshlrev_b32_e32 v82, 2, v82
	v_xor_b32_e32 v82, 64, v82
	ds_bpermute_b32 v82, v82, v86
	s_waitcnt lgkmcnt(0)
	v_add_f32_e32 v82, v86, v82
	v_mov_b32_e32 v83, v82
	s_nop 1
	v_permlane32_swap_b32_e32 v83, v82
	s_and_saveexec_b64 s[24:25], s[2:3]
	s_cbranch_execz .LBB0_2535
	v_lshlrev_b64 v[84:85], 6, v[106:107]
	v_lshl_add_u64 v[84:85], s[22:23], 0, v[84:85]
	s_waitcnt lgkmcnt(0)
	v_add_f32_e32 v82, v82, v83
	global_store_dword v[84:85], v82, off

.LBB0_2553:
	v_mov_b32_e32 v66, v1
	v_mbcnt_lo_u32_b32 v66, -1, v66
	v_mbcnt_hi_u32_b32 v66, -1, v66
	v_lshlrev_b32_e32 v66, 2, v66
	v_xor_b32_e32 v66, 64, v66
	ds_bpermute_b32 v66, v66, v70
	s_waitcnt lgkmcnt(0)
	v_add_f32_e32 v66, v70, v66
	v_mov_b32_e32 v67, v66
	s_nop 1
	v_permlane32_swap_b32_e32 v67, v66
	s_and_saveexec_b64 s[24:25], s[2:3]
	s_cbranch_execz .LBB0_2555
	v_lshlrev_b64 v[68:69], 6, v[90:91]
	v_lshl_add_u64 v[68:69], s[22:23], 0, v[68:69]
	s_waitcnt lgkmcnt(0)
	v_add_f32_e32 v66, v66, v67
	global_store_dword v[68:69], v66, off

.LBB0_2573:
	v_mov_b32_e32 v50, v1
	v_mbcnt_lo_u32_b32 v50, -1, v50
	v_mbcnt_hi_u32_b32 v50, -1, v50
	v_lshlrev_b32_e32 v50, 2, v50
	v_xor_b32_e32 v50, 64, v50
	ds_bpermute_b32 v50, v50, v54
	s_waitcnt lgkmcnt(0)
	v_add_f32_e32 v50, v54, v50
	v_mov_b32_e32 v51, v50
	s_nop 1
	v_permlane32_swap_b32_e32 v51, v50
	s_and_saveexec_b64 s[24:25], s[2:3]
	s_cbranch_execz .LBB0_2575
	v_lshlrev_b64 v[52:53], 6, v[76:77]
	v_lshl_add_u64 v[52:53], s[22:23], 0, v[52:53]
	s_waitcnt lgkmcnt(0)
	v_add_f32_e32 v50, v50, v51
	global_store_dword v[52:53], v50, off

.LBB0_2593:
	v_mov_b32_e32 v34, v1
	v_mbcnt_lo_u32_b32 v34, -1, v34
	v_mbcnt_hi_u32_b32 v34, -1, v34
	v_lshlrev_b32_e32 v34, 2, v34
	v_xor_b32_e32 v34, 64, v34
	ds_bpermute_b32 v34, v34, v38
	s_waitcnt lgkmcnt(0)
	v_add_f32_e32 v34, v38, v34
	v_mov_b32_e32 v35, v34
	s_nop 1
	v_permlane32_swap_b32_e32 v35, v34
	s_and_saveexec_b64 s[24:25], s[2:3]
	s_cbranch_execz .LBB0_2595
	v_lshlrev_b64 v[36:37], 6, v[58:59]
	v_lshl_add_u64 v[36:37], s[22:23], 0, v[36:37]
	s_waitcnt lgkmcnt(0)
	v_add_f32_e32 v34, v34, v35
	global_store_dword v[36:37], v34, off

.LBB0_2613:
	v_mov_b32_e32 v18, v1
	v_mbcnt_lo_u32_b32 v18, -1, v18
	v_mbcnt_hi_u32_b32 v18, -1, v18
	v_lshlrev_b32_e32 v18, 2, v18
	v_xor_b32_e32 v18, 64, v18
	ds_bpermute_b32 v18, v18, v22
	s_waitcnt lgkmcnt(0)
	v_add_f32_e32 v18, v22, v18
	v_mov_b32_e32 v19, v18
	s_nop 1
	v_permlane32_swap_b32_e32 v19, v18
	s_and_saveexec_b64 s[24:25], s[2:3]
	s_cbranch_execz .LBB0_2615
	v_lshlrev_b64 v[20:21], 6, v[42:43]
	v_lshl_add_u64 v[20:21], s[22:23], 0, v[20:21]
	s_waitcnt lgkmcnt(0)
	v_add_f32_e32 v18, v18, v19
	global_store_dword v[20:21], v18, off

.LBB0_2631:
	v_mov_b32_e32 v2, v1
	v_mbcnt_lo_u32_b32 v2, -1, v2
	v_mbcnt_hi_u32_b32 v2, -1, v2
	v_lshlrev_b32_e32 v2, 2, v2
	v_xor_b32_e32 v2, 64, v2
	ds_bpermute_b32 v2, v2, v6
	s_waitcnt lgkmcnt(0)
	v_add_f32_e32 v2, v6, v2
	v_mov_b32_e32 v3, v2
	s_nop 1
	v_permlane32_swap_b32_e32 v3, v2
	s_and_saveexec_b64 s[6:7], s[2:3]
	s_cbranch_execz .LBB0_2633
	v_lshlrev_b64 v[4:5], 6, v[18:19]
	v_lshl_add_u64 v[4:5], s[22:23], 0, v[4:5]
	s_waitcnt lgkmcnt(0)
	v_add_f32_e32 v2, v2, v3
	global_store_dword v[4:5], v2, off
